# attention: max3 tree, batched compressed-branch bias lookups, removed two redundant vmcnt0 waits, hoisted SGU norm-param loads
# speedup vs baseline: 1.0002x; 1.0002x over previous
; #define OPQ_V(x) asm volatile("" : "+v"(x))
; __device__ __forceinline__ int t5_bucket(int d) {
;     if (d < 16) return d;
;     int b = 16;
;     b += (d >= 19) + (d >= 21) + (d >= 24) + (d >= 27) + (d >= 31) + (d >= 35) + (d >= 40) + (d >= 46) + (d >= 52) + (d >= 59) + (d >= 67) + (d >= 77) + (d >= 87) + (d >= 99) + (d >= 113);
;     return b;
; __device__ __forceinline__ void attn_unit(int bg, int pb, bool build, const bf16* Q, const bf16* KV, const bf16* KCN, const bf16* VCT, const float* GATES, const float* rel_bias, bf16* A, unsigned char* lds) {
;     int tid_ = threadIdx.x; OPQ_V(tid_); const int tid = tid_, lane = tid & 63, w = __builtin_amdgcn_readfirstlane(tid >> 6), qi = lane & 15, q4 = lane >> 4;
;     const int hl = w & 3, half = w >> 2, b = bg >> 2, g = bg & 3, head = g * 4 + hl;
;     const int p0 = pb * 32 + half * 16, t = p0 + qi; const size_t tok = (size_t)b * 2048 + t;
;     float* biasT = (float*)(lds + AL_BIAS); float* impA = (float*)(lds + AL_IMPA); float* impB = (float*)(lds + AL_IMPB); float* impT = (float*)(lds + AL_IMPT); unsigned* selw = (unsigned*)(lds + AL_SELM);
;     const bf16x8 qf0 = *(const bf16x8*)(Q + tok * 1024 + head * 64 + q4 * 8), qf1 = *(const bf16x8*)(Q + tok * 1024 + head * 64 + 32 + q4 * 8);
;     const float g0 = GATES[tok * 48 + head * 3 + 0], g1 = GATES[tok * 48 + head * 3 + 1], g2 = GATES[tok * 48 + head * 3 + 2];
;     if (tid < 32) selw[tid] = 0u;
;     if (build) {
;         const int h_ = tid >> 7, d_ = tid & 127; if (d_ < BIAS_N) biasT[h_ * 128 + d_] = rel_bias[t5_bucket(d_) * 16 + g * 4 + h_] * LOG2E;
.LBB0_241:
	s_lshl_b32 s0, s2, 1
	s_and_b32 s0, s0, 14
	s_bfe_u32 s1, s2, 0x10007
	v_mov_b32_e32 v60, v202
	s_or_b32 s69, s0, s1
	s_lshl_b32 s96, s88, 5
	v_readfirstlane_b32 s0, v60
	s_bfe_u32 s12, s0, 0x20006
	s_ashr_i32 s0, s0, 4
	s_and_b32 s75, s0, -16
	v_and_b32_e32 v58, 15, v60
	s_add_i32 s80, s75, s96
	v_or_b32_e32 v126, s80, v58
	s_lshl_b32 s0, s2, 10
	s_lshl_b32 s1, s69, 2
	s_and_b32 s38, s0, 0x1800
	v_ashrrev_i32_e32 v127, 31, v126
	s_and_b32 s11, s1, 12
	v_lshl_add_u64 v[6:7], v[126:127], 0, s[38:39]
	v_readlane_b32 s0, v255, 30
	s_or_b32 s10, s12, s11
	s_waitcnt lgkmcnt(0)
	v_lshlrev_b64 v[2:3], 11, v[6:7]
	v_readlane_b32 s1, v255, 31
	v_bfe_u32 v59, v60, 4, 2
	s_lshl_b32 s38, s10, 7
	v_lshl_add_u64 v[2:3], s[0:1], 0, v[2:3]
	v_lshl_add_u64 v[2:3], v[2:3], 0, s[38:39]
	v_lshlrev_b32_e32 v0, 4, v59
	v_readlane_b32 s0, v255, 36
	v_lshl_add_u64 v[2:3], v[2:3], 0, v[0:1]
	v_readlane_b32 s1, v255, 37
	global_load_dwordx4 v[18:21], v[2:3], off
	global_load_dwordx4 v[22:25], v[2:3], off offset:64
	v_mov_b64_e32 v[2:3], s[0:1]
	s_movk_i32 s7, 0xc0
	v_mad_u64_u32 v[2:3], s[0:1], v6, s7, v[2:3]
	v_mad_i32_i24 v3, v7, s7, v3
	s_mul_i32 s38, s10, 12
	v_lshl_add_u64 v[2:3], v[2:3], 0, s[38:39]
	global_load_dwordx3 v[122:124], v[2:3], off
	v_cmp_gt_i32_e32 vcc, 32, v60
	s_and_saveexec_b64 s[0:1], vcc
	v_lshl_add_u32 v0, v60, 2, 0
	ds_write_b32 v0, v1 offset:38912
	s_or_b64 exec, exec, s[0:1]
	s_cmp_eq_u32 s69, s6
	s_cbranch_scc1 .LBB0_249
	v_and_b32_e32 v0, 0x7f, v60
	s_movk_i32 s0, 0x72
	v_cmp_gt_u32_e32 vcc, s0, v0
	s_and_saveexec_b64 s[0:1], vcc
	s_cbranch_execz .LBB0_248
	v_cmp_lt_u32_e32 vcc, 15, v0
	s_and_saveexec_b64 s[6:7], vcc
	s_cbranch_execz .LBB0_247
	v_cmp_lt_u32_e32 vcc, 18, v0
	s_movk_i32 s13, 0x4c
	s_nop 0
	v_cndmask_b32_e64 v2, 0, 1, vcc
	v_cmp_lt_u32_e32 vcc, 26, v0
	s_nop 1
	v_cndmask_b32_e64 v3, 0, 1, vcc
	v_cmp_lt_u32_e32 vcc, 34, v0
	s_nop 1
	v_cndmask_b32_e64 v4, 0, 1, vcc
	v_cmp_lt_u32_e32 vcc, 45, v0
	s_nop 1
	v_cndmask_b32_e64 v5, 0, 1, vcc
	v_cmp_lt_u32_e32 vcc, 58, v0
	s_nop 1
	v_cndmask_b32_e64 v8, 0, 1, vcc
	v_cmp_lt_u32_e32 vcc, s13, v0
	s_movk_i32 s13, 0x62
	s_nop 0
	v_cndmask_b32_e64 v9, 0, 1, vcc
	v_cmp_lt_u32_e32 vcc, s13, v0
	s_movk_i32 s13, 0x42
	s_nop 0
	v_cndmask_b32_e64 v10, 0, 1, vcc
	v_cmp_lt_u32_e32 vcc, 20, v0
	s_nop 1
	v_cndmask_b32_e64 v11, 16, 17, vcc
	v_cmp_lt_u32_e32 vcc, 23, v0
	s_nop 1
	v_addc_co_u32_e32 v2, vcc, v11, v2, vcc
	v_cmp_lt_u32_e32 vcc, 30, v0
	s_nop 1
	v_addc_co_u32_e32 v2, vcc, v2, v3, vcc
	v_cmp_lt_u32_e32 vcc, 39, v0
	s_nop 1
	v_addc_co_u32_e32 v2, vcc, v2, v4, vcc
	v_cmp_lt_u32_e32 vcc, 51, v0
	s_nop 1
	v_addc_co_u32_e32 v2, vcc, v2, v5, vcc
	v_cmp_lt_u32_e32 vcc, s13, v0
	s_movk_i32 s13, 0x56
	s_nop 0
	v_addc_co_u32_e32 v2, vcc, v2, v8, vcc
	v_cmp_lt_u32_e32 vcc, s13, v0
	s_movk_i32 s13, 0x71
	s_nop 0
	v_addc_co_u32_e32 v2, vcc, v2, v9, vcc
	v_cmp_eq_u32_e32 vcc, s13, v0
	s_nop 1
	v_addc_co_u32_e32 v0, vcc, v2, v10, vcc

; __device__ __forceinline__ void attn_unit(int bg, int pb, bool build, const bf16* Q, const bf16* KV, const bf16* KCN, const bf16* VCT, const float* GATES, const float* rel_bias, bf16* A, unsigned char* lds) {
;     ...
;         const int nst = (2 * pb + 1 + 31) >> 5;
;         float pc[4][2][4];
; #pragma unroll
;         for (int st = 0; st < 4; ++st)
; #pragma unroll
;             for (int ph = 0; ph < 2; ++ph)
; #pragma unroll
;                 for (int j = 0; j < 4; ++j) pc[st][ph][j] = NEGF;
;         float mx = NEGF;
; #pragma unroll
;         for (int st = 0; st < 4; ++st) if (st < nst) {
; #pragma unroll
;             for (int ph = 0; ph < 2; ++ph) {
;                 const bf16* kp = (const bf16*)(lds + AL_CK + (st * 32 + ph * 16 + qi) * CKP) + q4 * 8;
;                 const bf16x8 a0 = *(const bf16x8*)kp, a1 = *(const bf16x8*)(kp + 32);
;                 f32x4 s = {0.f, 0.f, 0.f, 0.f};
;                 s = __builtin_amdgcn_mfma_f32_16x16x32_bf16(a0, qf0, s, 0, 0, 0); s = __builtin_amdgcn_mfma_f32_16x16x32_bf16(a1, qf1, s, 0, 0, 0);
; #pragma unroll
;                 for (int j = 0; j < 4; ++j) {
;                     const int c = st * 32 + ph * 16 + q4 * 4 + j, dist = t - (16 * c + 31);
;                     const int bi = dist < 0 ? 0 : (dist > BIAS_N - 1 ? BIAS_N - 1 : dist);
;                     const float l = s[j] * SC2 + bias[bi];
;                     if (dist >= 0) { pc[st][ph][j] = l; mx = fmaxf(mx, l); }
;                 }
;             }
;         }
.LBB0_249:
	s_lshl_b32 s0, s12, 9
	v_lshlrev_b32_e32 v0, 3, v59
	s_add_i32 s85, s0, 0
	v_readlane_b32 s0, v254, 49
	v_mov_b32_e32 v2, s85
	ds_read_b32 v130, v2 offset:452
	v_lshl_add_u32 v10, v0, 1, s0
	s_movk_i32 s0, 0x90
	v_mad_u32_u24 v8, v58, s0, v10
	s_lshr_b32 s38, s2, 7
	s_lshl_b32 s74, s10, 6
	v_lshlrev_b64 v[128:129], 10, v[6:7]
	v_lshlrev_b32_e32 v8, 6, v59
	v_sub_u32_e32 v9, v126, v8
	v_mul_u32_u24_e32 v61, 0x90, v58
	v_add_u32_e32 v10, v10, v61
	s_cmp_gt_u32 s88, 15
	s_cselect_b64 s[86:87], -1, 0
	s_cmp_gt_u32 s88, 31
	s_cselect_b64 s[0:1], -1, 0
	s_cmp_gt_u32 s88, 47
	s_cselect_b64 s[6:7], -1, 0
	v_mov_b32_e32 v8, 0xf149f2ca
	v_mov_b32_e32 v244, 0xf149f2ca
	ds_read_b128 v[180:183], v10 offset:0
	ds_read_b128 v[184:187], v10 offset:64
	ds_read_b128 v[188:191], v10 offset:2304
	ds_read_b128 v[192:195], v10 offset:2368
	v_subrev_u32_e32 v196, 31, v9
	v_subrev_u32_e32 v197, 47, v9
	v_subrev_u32_e32 v198, 63, v9
	v_subrev_u32_e32 v199, 0x4f, v9
	v_subrev_u32_e32 v220, 0x11f, v9
	v_subrev_u32_e32 v221, 0x12f, v9
	v_subrev_u32_e32 v222, 0x13f, v9
	v_subrev_u32_e32 v223, 0x14f, v9
	v_med3_i32 v196, v196, 0, v227
	v_med3_i32 v197, v197, 0, v227
	v_med3_i32 v198, v198, 0, v227
	v_med3_i32 v199, v199, 0, v227
	v_med3_i32 v220, v220, 0, v227
	v_med3_i32 v221, v221, 0, v227
	v_med3_i32 v222, v222, 0, v227
	v_med3_i32 v223, v223, 0, v227
	v_lshl_add_u32 v196, v196, 2, s85
	v_lshl_add_u32 v197, v197, 2, s85
	v_lshl_add_u32 v198, v198, 2, s85
	v_lshl_add_u32 v199, v199, 2, s85
	v_lshl_add_u32 v220, v220, 2, s85
	v_lshl_add_u32 v221, v221, 2, s85
	v_lshl_add_u32 v222, v222, 2, s85
	v_lshl_add_u32 v223, v223, 2, s85
	ds_read_b32 v196, v196
	ds_read_b32 v197, v197
	ds_read_b32 v198, v198
	ds_read_b32 v199, v199
	ds_read_b32 v220, v220
	ds_read_b32 v221, v221
	ds_read_b32 v222, v222
	ds_read_b32 v223, v223
	s_waitcnt vmcnt(2) lgkmcnt(11)
	v_mfma_f32_16x16x32_bf16 v[2:5], v[180:183], v[18:21], 0
	s_waitcnt vmcnt(1) lgkmcnt(10)
	v_mfma_f32_16x16x32_bf16 v[2:5], v[184:187], v[22:25], v[2:5]
	s_waitcnt lgkmcnt(9)
	v_mfma_f32_16x16x32_bf16 v[240:243], v[188:191], v[18:21], 0
	s_waitcnt lgkmcnt(8)
	v_mfma_f32_16x16x32_bf16 v[240:243], v[192:195], v[22:25], v[240:243]
	s_waitcnt lgkmcnt(0)
	s_nop 7
	v_cmp_lt_i32_e32 vcc, 30, v9
	v_fmac_f32_e32 v196, 0x3e38aa3b, v2
	s_nop 0
	v_cndmask_b32_e32 v15, v244, v196, vcc
	v_cmp_lt_i32_e32 vcc, 46, v9
	v_fmac_f32_e32 v197, 0x3e38aa3b, v3
	v_max_f32_e32 v8, v8, v15
	v_cndmask_b32_e32 v14, v244, v197, vcc
	v_cmp_lt_i32_e32 vcc, 62, v9
	v_fmac_f32_e32 v198, 0x3e38aa3b, v4
	v_max_f32_e32 v8, v8, v14
	v_cndmask_b32_e32 v26, v244, v198, vcc
	v_cmp_lt_i32_e32 vcc, 0x4e, v9
	v_fmac_f32_e32 v199, 0x3e38aa3b, v5
	v_max_f32_e32 v8, v8, v26
	v_cndmask_b32_e32 v27, v244, v199, vcc
	v_cmp_lt_i32_e32 vcc, 0x11e, v9
	v_fmac_f32_e32 v220, 0x3e38aa3b, v240
	v_max_f32_e32 v8, v8, v27
	v_cndmask_b32_e32 v28, v244, v220, vcc
	v_cmp_lt_i32_e32 vcc, 0x12e, v9
	v_fmac_f32_e32 v221, 0x3e38aa3b, v241
	v_max_f32_e32 v8, v8, v28
	v_cndmask_b32_e32 v29, v244, v221, vcc
	v_cmp_lt_i32_e32 vcc, 0x13e, v9
	v_fmac_f32_e32 v222, 0x3e38aa3b, v242
	v_max_f32_e32 v8, v8, v29
	v_cndmask_b32_e32 v30, v244, v222, vcc
	v_cmp_lt_i32_e32 vcc, 0x14e, v9
	v_fmac_f32_e32 v223, 0x3e38aa3b, v243
	v_max_f32_e32 v8, v8, v30
	v_cndmask_b32_e32 v31, v244, v223, vcc
	v_max_f32_e32 v8, v8, v31
	s_cmp_lt_u32 s88, 16
	s_cbranch_scc1 .Lcmp_skip1
	ds_read_b128 v[180:183], v10 offset:4608
	ds_read_b128 v[184:187], v10 offset:4672
	ds_read_b128 v[188:191], v10 offset:6912
	ds_read_b128 v[192:195], v10 offset:6976
	v_subrev_u32_e32 v196, 0x21f, v9
	v_subrev_u32_e32 v197, 0x22f, v9
	v_subrev_u32_e32 v198, 0x23f, v9
	v_subrev_u32_e32 v199, 0x24f, v9
	v_subrev_u32_e32 v220, 0x31f, v9
	v_subrev_u32_e32 v221, 0x32f, v9
	v_subrev_u32_e32 v222, 0x33f, v9
	v_subrev_u32_e32 v223, 0x34f, v9
	v_med3_i32 v196, v196, 0, v227
	v_med3_i32 v197, v197, 0, v227
	v_med3_i32 v198, v198, 0, v227
	v_med3_i32 v199, v199, 0, v227
	v_med3_i32 v220, v220, 0, v227
	v_med3_i32 v221, v221, 0, v227
	v_med3_i32 v222, v222, 0, v227
	v_med3_i32 v223, v223, 0, v227
	v_lshl_add_u32 v196, v196, 2, s85
	v_lshl_add_u32 v197, v197, 2, s85
	v_lshl_add_u32 v198, v198, 2, s85
	v_lshl_add_u32 v199, v199, 2, s85
	v_lshl_add_u32 v220, v220, 2, s85
	v_lshl_add_u32 v221, v221, 2, s85
	v_lshl_add_u32 v222, v222, 2, s85
	v_lshl_add_u32 v223, v223, 2, s85
	ds_read_b32 v196, v196
	ds_read_b32 v197, v197
	ds_read_b32 v198, v198
	ds_read_b32 v199, v199
	ds_read_b32 v220, v220
	ds_read_b32 v221, v221
	ds_read_b32 v222, v222
	ds_read_b32 v223, v223
	s_waitcnt lgkmcnt(11)
	v_mfma_f32_16x16x32_bf16 v[2:5], v[180:183], v[18:21], 0
	s_waitcnt lgkmcnt(10)
	v_mfma_f32_16x16x32_bf16 v[2:5], v[184:187], v[22:25], v[2:5]
	s_waitcnt lgkmcnt(9)
	v_mfma_f32_16x16x32_bf16 v[240:243], v[188:191], v[18:21], 0
	s_waitcnt lgkmcnt(8)
	v_mfma_f32_16x16x32_bf16 v[240:243], v[192:195], v[22:25], v[240:243]
	s_waitcnt lgkmcnt(0)
	s_nop 7
	v_cmp_lt_i32_e32 vcc, 0x21e, v9
	v_fmac_f32_e32 v196, 0x3e38aa3b, v2
	s_nop 0
	v_cndmask_b32_e32 v33, v244, v196, vcc
	v_cmp_lt_i32_e32 vcc, 0x22e, v9
	v_fmac_f32_e32 v197, 0x3e38aa3b, v3
	v_max_f32_e32 v8, v8, v33
	v_cndmask_b32_e32 v32, v244, v197, vcc
	v_cmp_lt_i32_e32 vcc, 0x23e, v9
	v_fmac_f32_e32 v198, 0x3e38aa3b, v4
	v_max_f32_e32 v8, v8, v32
	v_cndmask_b32_e32 v34, v244, v198, vcc
	v_cmp_lt_i32_e32 vcc, 0x24e, v9
	v_fmac_f32_e32 v199, 0x3e38aa3b, v5
	v_max_f32_e32 v8, v8, v34
	v_cndmask_b32_e32 v35, v244, v199, vcc
	v_cmp_lt_i32_e32 vcc, 0x31e, v9
	v_fmac_f32_e32 v220, 0x3e38aa3b, v240
	v_max_f32_e32 v8, v8, v35
	v_cndmask_b32_e32 v36, v244, v220, vcc
	v_cmp_lt_i32_e32 vcc, 0x32e, v9
	v_fmac_f32_e32 v221, 0x3e38aa3b, v241
	v_max_f32_e32 v8, v8, v36
	v_cndmask_b32_e32 v37, v244, v221, vcc
	v_cmp_lt_i32_e32 vcc, 0x33e, v9
	v_fmac_f32_e32 v222, 0x3e38aa3b, v242
	v_max_f32_e32 v8, v8, v37
	v_cndmask_b32_e32 v38, v244, v222, vcc
	v_cmp_lt_i32_e32 vcc, 0x34e, v9
	v_fmac_f32_e32 v223, 0x3e38aa3b, v243
	v_max_f32_e32 v8, v8, v38
	v_cndmask_b32_e32 v39, v244, v223, vcc
	v_max_f32_e32 v8, v8, v39
	s_cmp_lt_u32 s88, 32
	s_cbranch_scc1 .Lcmp_skip2
; __device__ __forceinline__ void attn_unit(int bg, int pb, bool build, const bf16* Q, const bf16* KV, const bf16* KCN, const bf16* VCT, const float* GATES, const float* rel_bias, bf16* A, unsigned char* lds) {
;     ...
;         for (int st = 0; st < 4; ++st) if (st < nst) {
; #pragma unroll
;             for (int ph = 0; ph < 2; ++ph) {
;                 const bf16* kp = (const bf16*)(lds + AL_CK + (st * 32 + ph * 16 + qi) * CKP) + q4 * 8;
;                 const bf16x8 a0 = *(const bf16x8*)kp, a1 = *(const bf16x8*)(kp + 32);
;                 f32x4 s = {0.f, 0.f, 0.f, 0.f};
;                 s = __builtin_amdgcn_mfma_f32_16x16x32_bf16(a0, qf0, s, 0, 0, 0); s = __builtin_amdgcn_mfma_f32_16x16x32_bf16(a1, qf1, s, 0, 0, 0);
; #pragma unroll
;                 for (int j = 0; j < 4; ++j) {
;                     const int c = st * 32 + ph * 16 + q4 * 4 + j, dist = t - (16 * c + 31);
;                     const int bi = dist < 0 ? 0 : (dist > BIAS_N - 1 ? BIAS_N - 1 : dist);
;                     const float l = s[j] * SC2 + bias[bi];
;                     if (dist >= 0) { pc[st][ph][j] = l; mx = fmaxf(mx, l); }
;                 }
;             }
;         }
	ds_read_b128 v[180:183], v10 offset:9216
	ds_read_b128 v[184:187], v10 offset:9280
	ds_read_b128 v[188:191], v10 offset:11520
	ds_read_b128 v[192:195], v10 offset:11584
	v_subrev_u32_e32 v196, 0x41f, v9
	v_subrev_u32_e32 v197, 0x42f, v9
	v_subrev_u32_e32 v198, 0x43f, v9
	v_subrev_u32_e32 v199, 0x44f, v9
	v_subrev_u32_e32 v220, 0x51f, v9
	v_subrev_u32_e32 v221, 0x52f, v9
	v_subrev_u32_e32 v222, 0x53f, v9
	v_subrev_u32_e32 v223, 0x54f, v9
	v_med3_i32 v196, v196, 0, v227
	v_med3_i32 v197, v197, 0, v227
	v_med3_i32 v198, v198, 0, v227
	v_med3_i32 v199, v199, 0, v227
	v_med3_i32 v220, v220, 0, v227
	v_med3_i32 v221, v221, 0, v227
	v_med3_i32 v222, v222, 0, v227
	v_med3_i32 v223, v223, 0, v227
	v_lshl_add_u32 v196, v196, 2, s85
	v_lshl_add_u32 v197, v197, 2, s85
	v_lshl_add_u32 v198, v198, 2, s85
	v_lshl_add_u32 v199, v199, 2, s85
	v_lshl_add_u32 v220, v220, 2, s85
	v_lshl_add_u32 v221, v221, 2, s85
	v_lshl_add_u32 v222, v222, 2, s85
	v_lshl_add_u32 v223, v223, 2, s85
	ds_read_b32 v196, v196
	ds_read_b32 v197, v197
	ds_read_b32 v198, v198
	ds_read_b32 v199, v199
	ds_read_b32 v220, v220
	ds_read_b32 v221, v221
	ds_read_b32 v222, v222
	ds_read_b32 v223, v223
	s_waitcnt lgkmcnt(11)
	v_mfma_f32_16x16x32_bf16 v[2:5], v[180:183], v[18:21], 0
	s_waitcnt lgkmcnt(10)
	v_mfma_f32_16x16x32_bf16 v[2:5], v[184:187], v[22:25], v[2:5]
	s_waitcnt lgkmcnt(9)
	v_mfma_f32_16x16x32_bf16 v[240:243], v[188:191], v[18:21], 0
	s_waitcnt lgkmcnt(8)
	v_mfma_f32_16x16x32_bf16 v[240:243], v[192:195], v[22:25], v[240:243]
	s_waitcnt lgkmcnt(0)
	s_nop 7
	v_cmp_lt_i32_e32 vcc, 0x41e, v9
	v_fmac_f32_e32 v196, 0x3e38aa3b, v2
	s_nop 0
	v_cndmask_b32_e32 v7, v244, v196, vcc
	v_cmp_lt_i32_e32 vcc, 0x42e, v9
	v_fmac_f32_e32 v197, 0x3e38aa3b, v3
	v_max_f32_e32 v8, v8, v7
	v_cndmask_b32_e32 v6, v244, v197, vcc
	v_cmp_lt_i32_e32 vcc, 0x43e, v9
	v_fmac_f32_e32 v198, 0x3e38aa3b, v4
	v_max_f32_e32 v8, v8, v6
	v_cndmask_b32_e32 v16, v244, v198, vcc
	v_cmp_lt_i32_e32 vcc, 0x44e, v9
	v_fmac_f32_e32 v199, 0x3e38aa3b, v5
	v_max_f32_e32 v8, v8, v16
	v_cndmask_b32_e32 v12, v244, v199, vcc
	v_cmp_lt_i32_e32 vcc, 0x51e, v9
	v_fmac_f32_e32 v220, 0x3e38aa3b, v240
	v_max_f32_e32 v8, v8, v12
	v_cndmask_b32_e32 v40, v244, v220, vcc
	v_cmp_lt_i32_e32 vcc, 0x52e, v9
	v_fmac_f32_e32 v221, 0x3e38aa3b, v241
	v_max_f32_e32 v8, v8, v40
	v_cndmask_b32_e32 v17, v244, v221, vcc
	v_cmp_lt_i32_e32 vcc, 0x53e, v9
	v_fmac_f32_e32 v222, 0x3e38aa3b, v242
	v_max_f32_e32 v8, v8, v17
	v_cndmask_b32_e32 v42, v244, v222, vcc
	v_cmp_lt_i32_e32 vcc, 0x54e, v9
	v_fmac_f32_e32 v223, 0x3e38aa3b, v243
	v_max_f32_e32 v8, v8, v42
	v_cndmask_b32_e32 v41, v244, v223, vcc
	v_max_f32_e32 v8, v8, v41
	s_cmp_lt_u32 s88, 48
	s_cbranch_scc1 .Lcmp_skip3
	ds_read_b128 v[180:183], v10 offset:13824
	ds_read_b128 v[184:187], v10 offset:13888
	ds_read_b128 v[188:191], v10 offset:16128
	ds_read_b128 v[192:195], v10 offset:16192
	v_subrev_u32_e32 v196, 0x61f, v9
	v_subrev_u32_e32 v197, 0x62f, v9
	v_subrev_u32_e32 v198, 0x63f, v9
	v_subrev_u32_e32 v199, 0x64f, v9
	v_subrev_u32_e32 v220, 0x71f, v9
	v_subrev_u32_e32 v221, 0x72f, v9
	v_subrev_u32_e32 v222, 0x73f, v9
	v_subrev_u32_e32 v223, 0x74f, v9
	v_med3_i32 v196, v196, 0, v227
	v_med3_i32 v197, v197, 0, v227
	v_med3_i32 v198, v198, 0, v227
	v_med3_i32 v199, v199, 0, v227
	v_med3_i32 v220, v220, 0, v227
	v_med3_i32 v221, v221, 0, v227
	v_med3_i32 v222, v222, 0, v227
	v_med3_i32 v223, v223, 0, v227
	v_lshl_add_u32 v196, v196, 2, s85
	v_lshl_add_u32 v197, v197, 2, s85
	v_lshl_add_u32 v198, v198, 2, s85
	v_lshl_add_u32 v199, v199, 2, s85
	v_lshl_add_u32 v220, v220, 2, s85
	v_lshl_add_u32 v221, v221, 2, s85
	v_lshl_add_u32 v222, v222, 2, s85
	v_lshl_add_u32 v223, v223, 2, s85
	ds_read_b32 v196, v196
	ds_read_b32 v197, v197
	ds_read_b32 v198, v198
	ds_read_b32 v199, v199
	ds_read_b32 v220, v220
	ds_read_b32 v221, v221
	ds_read_b32 v222, v222
	ds_read_b32 v223, v223
	s_waitcnt lgkmcnt(11)
	v_mfma_f32_16x16x32_bf16 v[2:5], v[180:183], v[18:21], 0
	s_waitcnt lgkmcnt(10)
	v_mfma_f32_16x16x32_bf16 v[2:5], v[184:187], v[22:25], v[2:5]
	s_waitcnt lgkmcnt(9)
	v_mfma_f32_16x16x32_bf16 v[240:243], v[188:191], v[18:21], 0
	s_waitcnt lgkmcnt(8)
	v_mfma_f32_16x16x32_bf16 v[240:243], v[192:195], v[22:25], v[240:243]
	s_waitcnt lgkmcnt(0)
	s_nop 7
	v_cmp_lt_i32_e32 vcc, 0x61e, v9
	v_fmac_f32_e32 v196, 0x3e38aa3b, v2
	s_nop 0
	v_cndmask_b32_e32 v45, v244, v196, vcc
	v_cmp_lt_i32_e32 vcc, 0x62e, v9
	v_fmac_f32_e32 v197, 0x3e38aa3b, v3
	v_max_f32_e32 v8, v8, v45
	v_cndmask_b32_e32 v44, v244, v197, vcc
	v_cmp_lt_i32_e32 vcc, 0x63e, v9
	v_fmac_f32_e32 v198, 0x3e38aa3b, v4
	v_max_f32_e32 v8, v8, v44
	v_cndmask_b32_e32 v47, v244, v198, vcc
	v_cmp_lt_i32_e32 vcc, 0x64e, v9
	v_fmac_f32_e32 v199, 0x3e38aa3b, v5
	v_max_f32_e32 v8, v8, v47
	v_cndmask_b32_e32 v46, v244, v199, vcc
	v_cmp_lt_i32_e32 vcc, 0x71e, v9
	v_fmac_f32_e32 v220, 0x3e38aa3b, v240
	v_max_f32_e32 v8, v8, v46
	v_cndmask_b32_e32 v49, v244, v220, vcc
	v_cmp_lt_i32_e32 vcc, 0x72e, v9
	v_fmac_f32_e32 v221, 0x3e38aa3b, v241
	v_max_f32_e32 v8, v8, v49
	v_cndmask_b32_e32 v48, v244, v221, vcc
	v_cmp_lt_i32_e32 vcc, 0x73e, v9
	v_fmac_f32_e32 v222, 0x3e38aa3b, v242
	v_max_f32_e32 v8, v8, v48
	v_cndmask_b32_e32 v51, v244, v222, vcc
	v_cmp_lt_i32_e32 vcc, 0x74e, v9
	v_fmac_f32_e32 v223, 0x3e38aa3b, v243
	v_max_f32_e32 v8, v8, v51
	v_cndmask_b32_e32 v50, v244, v223, vcc
	v_max_f32_e32 v8, v8, v50
	s_branch .Lcmp_done
.Lcmp_skip1:
	v_mov_b32_e32 v33, 0xf149f2ca
	v_mov_b32_e32 v32, 0xf149f2ca
	v_mov_b32_e32 v34, 0xf149f2ca
	v_mov_b32_e32 v35, 0xf149f2ca
	v_mov_b32_e32 v36, 0xf149f2ca
	v_mov_b32_e32 v37, 0xf149f2ca
	v_mov_b32_e32 v38, 0xf149f2ca
	v_mov_b32_e32 v39, 0xf149f2ca
; __device__ __forceinline__ void attn_unit(int bg, int pb, bool build, const bf16* Q, const bf16* KV, const bf16* KCN, const bf16* VCT, const float* GATES, const float* rel_bias, bf16* A, unsigned char* lds) {
;     ...
;         mx = fmaxf(mx, __shfl_xor(mx, 16)); mx = fmaxf(mx, __shfl_xor(mx, 32));
;         float sum = 0.f;
; #pragma unroll
;         for (int st = 0; st < 4; ++st)
; #pragma unroll
;             for (int ph = 0; ph < 2; ++ph)
; #pragma unroll
;                 for (int j = 0; j < 4; ++j) { const float p = pc[st][ph][j] > -1e29f ? __builtin_amdgcn_exp2f(pc[st][ph][j] - mx) : 0.f; pc[st][ph][j] = p; sum += p; }
;         sum += __shfl_xor(sum, 16); sum += __shfl_xor(sum, 32);
.Lcmp_skip2:
	v_mov_b32_e32 v7, 0xf149f2ca
	v_mov_b32_e32 v6, 0xf149f2ca
	v_mov_b32_e32 v16, 0xf149f2ca
	v_mov_b32_e32 v12, 0xf149f2ca
	v_mov_b32_e32 v40, 0xf149f2ca
	v_mov_b32_e32 v17, 0xf149f2ca
	v_mov_b32_e32 v42, 0xf149f2ca
	v_mov_b32_e32 v41, 0xf149f2ca
.Lcmp_skip3:
	v_mov_b32_e32 v45, 0xf149f2ca
	v_mov_b32_e32 v44, 0xf149f2ca
	v_mov_b32_e32 v47, 0xf149f2ca
	v_mov_b32_e32 v46, 0xf149f2ca
	v_mov_b32_e32 v49, 0xf149f2ca
	v_mov_b32_e32 v48, 0xf149f2ca
	v_mov_b32_e32 v51, 0xf149f2ca
	v_mov_b32_e32 v50, 0xf149f2ca
.Lcmp_done:
.LBB0_322:
	v_and_b32_e32 v3, 64, v226
	v_xor_b32_e32 v2, 16, v226
	v_add_u32_e32 v3, 64, v3
	v_cmp_lt_i32_e32 vcc, v2, v3
	v_xor_b32_e32 v5, 32, v226
	v_max_f32_e32 v4, v8, v8
	v_cndmask_b32_e32 v2, v226, v2, vcc
	v_lshlrev_b32_e32 v136, 2, v2
	ds_bpermute_b32 v2, v136, v8
	v_cmp_lt_i32_e32 vcc, v5, v3
	s_lshl_b32 s10, s12, 5
	s_add_i32 s10, s10, s75
	v_cndmask_b32_e32 v3, v226, v5, vcc
	s_waitcnt lgkmcnt(0)
	v_max_f32_e32 v2, v2, v2
	v_max_f32_e32 v2, v4, v2
	v_lshlrev_b32_e32 v137, 2, v3
	ds_bpermute_b32 v3, v137, v2
	v_cmp_lt_f32_e32 vcc, s95, v6
	v_lshlrev_b32_e32 v138, 2, v59
	s_waitcnt lgkmcnt(0)
	v_max_f32_e32 v3, v3, v3
	v_max_f32_e32 v8, v2, v3
	v_sub_f32_e32 v2, v15, v8
	v_exp_f32_e32 v52, v2
	v_sub_f32_e32 v2, v26, v8
	v_exp_f32_e32 v62, v2
	v_sub_f32_e32 v2, v27, v8
	v_exp_f32_e32 v63, v2
	v_sub_f32_e32 v2, v28, v8
	v_exp_f32_e32 v64, v2
	v_sub_f32_e32 v2, v29, v8
	v_exp_f32_e32 v65, v2
	v_sub_f32_e32 v2, v30, v8
	v_exp_f32_e32 v66, v2
	v_sub_f32_e32 v2, v31, v8
	v_exp_f32_e32 v67, v2
	v_sub_f32_e32 v2, v33, v8
	v_exp_f32_e32 v56, v2
	v_sub_f32_e32 v2, v32, v8
	v_exp_f32_e32 v57, v2
	v_sub_f32_e32 v2, v34, v8
	v_exp_f32_e32 v54, v2
	v_sub_f32_e32 v2, v35, v8
	v_exp_f32_e32 v55, v2
	v_sub_f32_e32 v2, v36, v8
	v_exp_f32_e32 v68, v2
	v_sub_f32_e32 v2, v37, v8
	v_exp_f32_e32 v69, v2
	v_sub_f32_e32 v2, v38, v8
	v_exp_f32_e32 v70, v2
	v_sub_f32_e32 v2, v39, v8
	v_sub_f32_e32 v3, v14, v8
	v_exp_f32_e32 v71, v2
	v_sub_f32_e32 v2, v6, v8
	v_exp_f32_e32 v53, v3
	v_exp_f32_e32 v2, v2
	v_sub_f32_e32 v3, v7, v8
	v_exp_f32_e32 v3, v3
	v_sub_f32_e32 v5, v47, v8
	v_cndmask_b32_e32 v11, 0, v2, vcc
	v_cmp_lt_f32_e32 vcc, s95, v7
	v_sub_f32_e32 v2, v12, v8
	v_exp_f32_e32 v2, v2
	v_cndmask_b32_e32 v10, 0, v3, vcc
	v_sub_f32_e32 v3, v16, v8
	v_exp_f32_e32 v3, v3
	v_cmp_lt_f32_e32 vcc, s95, v12
	v_exp_f32_e32 v6, v5
	v_sub_f32_e32 v7, v49, v8
	v_cndmask_b32_e32 v13, 0, v2, vcc
	v_cmp_lt_f32_e32 vcc, s95, v16
	v_sub_f32_e32 v2, v17, v8
	v_exp_f32_e32 v2, v2
	v_cndmask_b32_e32 v12, 0, v3, vcc
	v_sub_f32_e32 v3, v40, v8
	v_exp_f32_e32 v3, v3
	v_cmp_lt_f32_e32 vcc, s95, v17
	v_exp_f32_e32 v9, v7
	s_nop 0
	v_cndmask_b32_e32 v17, 0, v2, vcc
	v_cmp_lt_f32_e32 vcc, s95, v40
	v_sub_f32_e32 v2, v41, v8
	v_exp_f32_e32 v2, v2
	v_cndmask_b32_e32 v16, 0, v3, vcc
	v_sub_f32_e32 v3, v42, v8
	v_exp_f32_e32 v3, v3
	v_cmp_lt_f32_e32 vcc, s95, v41
	s_nop 1
	v_cndmask_b32_e32 v43, 0, v2, vcc
	v_cmp_lt_f32_e32 vcc, s95, v42
	v_sub_f32_e32 v2, v44, v8
	v_exp_f32_e32 v2, v2
	v_cndmask_b32_e32 v42, 0, v3, vcc
	v_sub_f32_e32 v3, v45, v8
	v_exp_f32_e32 v4, v3
	v_cmp_lt_f32_e32 vcc, s95, v44
	s_nop 1
	v_cndmask_b32_e32 v3, 0, v2, vcc
	v_cmp_lt_f32_e32 vcc, s95, v45
	s_nop 1
	v_cndmask_b32_e32 v2, 0, v4, vcc
	v_sub_f32_e32 v4, v46, v8
	v_exp_f32_e32 v4, v4
	v_cmp_lt_f32_e32 vcc, s95, v46
	s_nop 1
	v_cndmask_b32_e32 v5, 0, v4, vcc
	v_cmp_lt_f32_e32 vcc, s95, v47
	s_nop 1
	v_cndmask_b32_e32 v4, 0, v6, vcc
	v_sub_f32_e32 v6, v48, v8
	v_exp_f32_e32 v6, v6
	v_cmp_lt_f32_e32 vcc, s95, v48
	s_nop 1
	v_cndmask_b32_e32 v7, 0, v6, vcc
	v_cmp_lt_f32_e32 vcc, s95, v49
	s_nop 1
	v_cndmask_b32_e32 v6, 0, v9, vcc
	v_sub_f32_e32 v9, v50, v8
	v_exp_f32_e32 v9, v9
	v_sub_f32_e32 v8, v51, v8
	v_exp_f32_e32 v8, v8
	v_cmp_lt_f32_e32 vcc, s95, v50
	s_nop 1
	v_cndmask_b32_e32 v9, 0, v9, vcc
	v_cmp_lt_f32_e32 vcc, s95, v51
	s_nop 1
	v_cndmask_b32_e32 v8, 0, v8, vcc
	v_cmp_lt_f32_e32 vcc, s95, v39
	s_nop 1
	v_cndmask_b32_e32 v51, 0, v71, vcc
	v_cmp_lt_f32_e32 vcc, s95, v38
	s_nop 1
	v_cndmask_b32_e32 v50, 0, v70, vcc
	v_cmp_lt_f32_e32 vcc, s95, v37
	s_nop 1
	v_cndmask_b32_e32 v49, 0, v69, vcc
	v_cmp_lt_f32_e32 vcc, s95, v36
	s_nop 1
	v_cndmask_b32_e32 v48, 0, v68, vcc
	v_cmp_lt_f32_e32 vcc, s95, v35
	s_nop 1
	v_cndmask_b32_e32 v55, 0, v55, vcc
	v_cmp_lt_f32_e32 vcc, s95, v34
	v_or_b32_e32 v34, s10, v58
	v_readlane_b32 s10, v254, 50
	v_cndmask_b32_e32 v54, 0, v54, vcc
	v_cmp_lt_f32_e32 vcc, s95, v32
	v_lshl_or_b32 v34, v34, 7, v138
	v_add_u32_e32 v38, 0, v34
	v_cndmask_b32_e32 v57, 0, v57, vcc
	v_cmp_lt_f32_e32 vcc, s95, v33
	s_nop 1
	v_cndmask_b32_e32 v56, 0, v56, vcc
	v_cmp_lt_f32_e32 vcc, s95, v31
	s_nop 1
	v_cndmask_b32_e32 v31, 0, v67, vcc
	v_cmp_lt_f32_e32 vcc, s95, v30
	s_nop 1
	v_cndmask_b32_e32 v30, 0, v66, vcc
	v_cmp_lt_f32_e32 vcc, s95, v29
	s_nop 1
	v_cndmask_b32_e32 v29, 0, v65, vcc
	v_cmp_lt_f32_e32 vcc, s95, v28
	s_nop 1
	v_cndmask_b32_e32 v28, 0, v64, vcc
	v_cmp_lt_f32_e32 vcc, s95, v27
	s_nop 1
	v_cndmask_b32_e32 v27, 0, v63, vcc
	v_cmp_lt_f32_e32 vcc, s95, v26
	s_nop 1
	v_cndmask_b32_e32 v26, 0, v62, vcc
	v_cmp_lt_f32_e32 vcc, s95, v15
	s_nop 1
	v_cndmask_b32_e32 v32, 0, v52, vcc
	v_cmp_lt_f32_e32 vcc, s95, v14
	v_add_f32_e32 v33, 0, v32
	v_add_u32_e32 v52, 0x800, v38
	v_cndmask_b32_e32 v15, 0, v53, vcc
	v_add_f32_e32 v14, v15, v33
	v_add_f32_e32 v14, v26, v14
	v_add_f32_e32 v14, v27, v14
	v_add_f32_e32 v14, v28, v14
	v_add_f32_e32 v14, v29, v14
	v_add_f32_e32 v14, v30, v14
	v_add_f32_e32 v14, v31, v14
	v_add_f32_e32 v14, v56, v14
	v_add_f32_e32 v14, v57, v14
	v_add_f32_e32 v14, v54, v14
	v_add_f32_e32 v14, v55, v14
	v_add_f32_e32 v14, v48, v14
	v_add_f32_e32 v14, v49, v14
	v_add_f32_e32 v14, v50, v14
	v_add_f32_e32 v14, v51, v14
	v_add_f32_e32 v14, v10, v14
	v_add_f32_e32 v14, v11, v14
	v_add_f32_e32 v14, v12, v14
	v_add_f32_e32 v14, v13, v14
	v_add_f32_e32 v14, v16, v14
	v_add_f32_e32 v14, v17, v14
	v_add_f32_e32 v14, v42, v14
	v_add_f32_e32 v14, v43, v14
	v_add_f32_e32 v14, v2, v14
	v_add_f32_e32 v14, v3, v14
	v_add_f32_e32 v14, v4, v14
	v_add_f32_e32 v14, v5, v14
	v_add_f32_e32 v14, v6, v14
	v_add_f32_e32 v14, v7, v14
	v_add_f32_e32 v14, v8, v14
	v_add_f32_e32 v14, v9, v14
	ds_bpermute_b32 v33, v136, v14
	v_add_u32_e32 v53, s10, v0
	s_waitcnt lgkmcnt(0)
; __device__ __forceinline__ bf16x8 pack_p(const float* a, const float* b) { u32x4 w; w.x = cvtpk(a[0], a[1]); w.y = cvtpk(a[2], a[3]); w.z = cvtpk(b[0], b[1]); w.w = cvtpk(b[2], b[3]); return __builtin_bit_cast(bf16x8, w); }
; __device__ __forceinline__ bf16x8 ldv(const bf16* p) { const s16x4 lo = *(const s16x4*)p, hi = *(const s16x4*)(p + 16); return __builtin_shufflevector(lo, hi, 0, 1, 2, 3, 4, 5, 6, 7); }
; __device__ __forceinline__ void attn_unit(int bg, int pb, bool build, const bf16* Q, const bf16* KV, const bf16* KCN, const bf16* VCT, const float* GATES, const float* rel_bias, bf16* A, unsigned char* lds) {
;     ...
;         sum += __shfl_xor(sum, 16); sum += __shfl_xor(sum, 32);
;         const float inv = sum > 0.f ? 1.f / sum : 0.f;
;         f32x4 oc[4];
; #pragma unroll
;         for (int dt = 0; dt < 4; ++dt) oc[dt] = (f32x4){0.f, 0.f, 0.f, 0.f};
;         const int prow = (hl * 32 + half * 16 + qi) * 32;
; #pragma unroll
;         for (int st = 0; st < 4; ++st) {
; #pragma unroll
;             for (int ph = 0; ph < 2; ++ph) {
; #pragma unroll
;                 for (int j = 0; j < 4; ++j) pc[st][ph][j] *= inv;
;                 const int jj = st * 8 + ph * 4 + q4;
;                 impA[prow + jj] = pc[st][ph][0] + pc[st][ph][1] + pc[st][ph][2] + 0.5f * pc[st][ph][3];
;                 impB[prow + jj] = 0.5f * pc[st][ph][3];
;             }
;             if (st < nst) {
;                 const bf16x8 pf = pack_p(pc[st][0], pc[st][1]);
; #pragma unroll
;                 for (int dt = 0; dt < 4; ++dt) { const bf16x8 vf = ldv((const bf16*)(lds + AL_CV + (dt * 16 + qi) * CVP) + st * 32 + q4 * 4); oc[dt] = __builtin_amdgcn_mfma_f32_16x16x32_bf16(vf, pf, oc[dt], 0, 0, 0); }
;             }
;         }
; #pragma unroll
;         for (int dt = 0; dt < 4; ++dt) acc[dt] = oc[dt] * g0;
	v_add_f32_e32 v14, v14, v33
	ds_bpermute_b32 v33, v137, v14
	s_waitcnt lgkmcnt(0)
	v_add_f32_e32 v0, v14, v33
	v_div_scale_f32 v14, s[10:11], v0, v0, 1.0
	v_rcp_f32_e32 v33, v14
	s_movk_i32 s10, 0x110
	v_mad_u32_u24 v44, v58, s10, v53
	v_fma_f32 v34, -v14, v33, 1.0
	v_fmac_f32_e32 v33, v34, v33
	v_div_scale_f32 v34, vcc, 1.0, v0, 1.0
	v_mul_f32_e32 v35, v34, v33
	v_fma_f32 v36, -v14, v35, v34
	v_fmac_f32_e32 v35, v36, v33
	v_fma_f32 v14, -v14, v35, v34
	v_div_fmas_f32 v14, v14, v33, v35
	v_div_fixup_f32 v14, v14, v0, 1.0
	v_cmp_lt_f32_e32 vcc, 0, v0
	s_nop 1
	v_cndmask_b32_e32 v14, 0, v14, vcc
	v_mov_b32_e32 v33, v14
	v_pk_mul_f32 v[34:35], v[26:27], v[14:15] op_sel_hi:[1,0]
	v_pk_mul_f32 v[32:33], v[14:15], v[32:33]
	v_mul_f32_e32 v15, 0.5, v35
	v_pk_mul_f32 v[36:37], v[28:29], v[14:15] op_sel_hi:[1,0]
	v_add_f32_e32 v0, v32, v33
	v_pk_mul_f32 v[30:31], v[30:31], v[14:15] op_sel_hi:[1,0]
	v_add_f32_e32 v26, v36, v37
	v_add_f32_e32 v0, v34, v0
	v_add_f32_e32 v26, v30, v26
	v_fmac_f32_e32 v0, 0.5, v35
	v_fmac_f32_e32 v26, 0.5, v31
	v_mul_f32_e32 v27, 0.5, v31
	ds_write2_b32 v52, v0, v26 offset1:4
	v_add_u32_e32 v0, 0x4800, v38
	ds_write2_b32 v0, v15, v27 offset1:4
	v_add_u32_e32 v15, 0x1000, v44
	v_cvt_pk_bf16_f32 v38, v32, v33
	v_cvt_pk_bf16_f32 v41, v30, v31
	ds_read2_b64 v[30:33], v15 offset0:32 offset1:36
	v_add_u32_e32 v15, 0x2000, v44
	v_cvt_pk_bf16_f32 v39, v34, v35
	v_cvt_pk_bf16_f32 v40, v36, v37
	ds_read2_b64 v[34:37], v15 offset0:64 offset1:68
	v_add_u32_e32 v15, 0x3000, v44
	ds_read2_b64 v[26:29], v44 offset1:4
	ds_read2_b64 v[44:47], v15 offset0:96 offset1:100
	v_mul_u32_u24_e32 v15, 0x110, v58
	s_waitcnt lgkmcnt(1)
	v_mfma_f32_16x16x32_bf16 v[26:29], v[26:29], v[38:41], 0
	v_mul_f32_e64 v48, v48, v14
	v_mul_f32_e64 v49, v49, v14
	v_pk_mul_f32 v[50:51], v[50:51], v[14:15] op_sel_hi:[1,0]
	s_andn2_b64 vcc, exec, s[86:87]
	v_mfma_f32_16x16x32_bf16 v[30:33], v[30:33], v[38:41], 0
	v_mfma_f32_16x16x32_bf16 v[34:37], v[34:37], v[38:41], 0
	s_waitcnt lgkmcnt(0)
	v_mfma_f32_16x16x32_bf16 v[38:41], v[44:47], v[38:41], 0
	v_mul_f32_e64 v44, v56, v14
	v_mul_f32_e64 v45, v57, v14
	v_pk_mul_f32 v[46:47], v[54:55], v[14:15] op_sel_hi:[1,0]
	v_add_f32_e32 v54, v44, v45
	v_add_f32_e32 v56, v48, v49
	v_add_f32_e32 v54, v46, v54
	v_add_f32_e32 v56, v50, v56
	v_fmac_f32_e32 v54, 0.5, v47
	v_fmac_f32_e32 v56, 0.5, v51
	v_mul_f32_e32 v55, 0.5, v47
	v_mul_f32_e32 v57, 0.5, v51
	ds_write2_b32 v52, v54, v56 offset0:8 offset1:12
	ds_write2_b32 v0, v55, v57 offset0:8 offset1:12
	v_add_u32_e32 v56, v53, v15
	v_add_u32_e32 v55, 0x1000, v56
	v_add_u32_e32 v54, 0x2000, v56
	v_add_u32_e32 v53, 0x3000, v56
	s_cbranch_vccnz .LBB0_324
	v_cvt_pk_bf16_f32 v44, v44, v45
	v_cvt_pk_bf16_f32 v45, v46, v47
	v_cvt_pk_bf16_f32 v46, v48, v49
	v_cvt_pk_bf16_f32 v47, v50, v51
	ds_read2_b64 v[48:51], v56 offset0:8 offset1:12
	s_waitcnt lgkmcnt(0)
	v_mfma_f32_16x16x32_bf16 v[26:29], v[48:51], v[44:47], v[26:29]
	ds_read2_b64 v[48:51], v55 offset0:40 offset1:44
	s_waitcnt lgkmcnt(0)
	v_mfma_f32_16x16x32_bf16 v[30:33], v[48:51], v[44:47], v[30:33]
	ds_read2_b64 v[48:51], v54 offset0:72 offset1:76
	s_waitcnt lgkmcnt(0)
	v_mfma_f32_16x16x32_bf16 v[34:37], v[48:51], v[44:47], v[34:37]
	ds_read2_b64 v[48:51], v53 offset0:104 offset1:108
	s_waitcnt lgkmcnt(0)
	v_mfma_f32_16x16x32_bf16 v[38:41], v[48:51], v[44:47], v[38:41]

; template <int MODE>
; __device__ __forceinline__ void attn_step(const unsigned char* sb, int st, const bf16x8 qf0, const bf16x8 qf1, int t, int p0, bool sel, const float* bias, float cfar, f32x4 (&o)[4], float& mrun, float& lrun,
;                                           int koff, int voff, int q4) {
;     ...
;     float mx = fmaxf(fmaxf(fmaxf(s[0][0], s[0][1]), fmaxf(s[0][2], s[0][3])), fmaxf(fmaxf(s[1][0], s[1][1]), fmaxf(s[1][2], s[1][3])));
;     mx = fmaxf(mx, fmaxf(fmaxf(fmaxf(s[2][0], s[2][1]), fmaxf(s[2][2], s[2][3])), fmaxf(fmaxf(s[3][0], s[3][1]), fmaxf(s[3][2], s[3][3]))));
;     mx = mx * fsc + fc;
;     mx = fmaxf(mx, __shfl_xor(mx, 16)); mx = fmaxf(mx, __shfl_xor(mx, 32));
;     const float mnew = fmaxf(mrun, mx);
;     f32x4 ps4 = {0.f, 0.f, 0.f, 0.f};
;     const float foff = fc - mnew;
; #pragma unroll
;     for (int kt = 0; kt < 4; ++kt) {
;         s[kt] = s[kt] * fsc + foff;
; #pragma unroll
;         for (int j = 0; j < 4; ++j) s[kt][j] = __builtin_amdgcn_exp2f(s[kt][j]);
;         ps4 += s[kt];
;     }
;     const float ps = (ps4.x + ps4.y) + (ps4.z + ps4.w);
;     if (__ballot(mnew != mrun) != 0ull) {
;         const float alpha = __builtin_amdgcn_exp2f(mrun - mnew);
;         lrun *= alpha;
; #pragma unroll
;         for (int dt = 0; dt < 4; ++dt) o[dt] *= alpha;
;     }
.LBB0_599:
	v_max3_f32 v119, v102, v103, v104
	v_max3_f32 v125, v105, v98, v99
	v_max3_f32 v127, v100, v101, v94
	v_max3_f32 v131, v95, v96, v97
	v_max3_f32 v119, v119, v125, v127
	v_max3_f32 v132, v90, v91, v92
	v_max3_f32 v131, v131, v132, v93
	v_max_f32_e32 v119, v119, v131
	v_fma_f32 v119, v114, v119, v121
	v_mov_b32_e32 v125, v119
	s_nop 1
	v_permlane16_swap_b32_e32 v125, v119
	v_max_f32_e32 v119, v119, v125
	v_mov_b32_e32 v125, v119
	s_nop 1
	v_permlane32_swap_b32_e32 v125, v119
	v_max3_f32 v119, v118, v119, v125
	v_cmp_neq_f32_e32 vcc, v119, v118
	s_cbranch_vccz .LBB0_601
	v_sub_f32_e32 v118, v118, v119
	v_exp_f32_e32 v118, v118
	s_nop 0
	v_mul_f32_e32 v117, v117, v118
	v_pk_mul_f32 v[56:57], v[56:57], v[118:119] op_sel_hi:[1,0]
	v_pk_mul_f32 v[54:55], v[54:55], v[118:119] op_sel_hi:[1,0]
	v_pk_mul_f32 v[52:53], v[52:53], v[118:119] op_sel_hi:[1,0]
	v_pk_mul_f32 v[50:51], v[50:51], v[118:119] op_sel_hi:[1,0]
	v_pk_mul_f32 v[44:45], v[44:45], v[118:119] op_sel_hi:[1,0]
	v_pk_mul_f32 v[42:43], v[42:43], v[118:119] op_sel_hi:[1,0]
	v_pk_mul_f32 v[48:49], v[48:49], v[118:119] op_sel_hi:[1,0]
	v_pk_mul_f32 v[46:47], v[46:47], v[118:119] op_sel_hi:[1,0]

; template <int MODE>
; __device__ __forceinline__ void attn_step(const unsigned char* sb, int st, const bf16x8 qf0, const bf16x8 qf1, int t, int p0, bool sel, const float* bias, float cfar, f32x4 (&o)[4], float& mrun, float& lrun,
;                                           int koff, int voff, int q4) {
;     ...
;     float mx = fmaxf(fmaxf(fmaxf(s[0][0], s[0][1]), fmaxf(s[0][2], s[0][3])), fmaxf(fmaxf(s[1][0], s[1][1]), fmaxf(s[1][2], s[1][3])));
;     mx = fmaxf(mx, fmaxf(fmaxf(fmaxf(s[2][0], s[2][1]), fmaxf(s[2][2], s[2][3])), fmaxf(fmaxf(s[3][0], s[3][1]), fmaxf(s[3][2], s[3][3]))));
;     mx = mx * fsc + fc;
;     mx = fmaxf(mx, __shfl_xor(mx, 16)); mx = fmaxf(mx, __shfl_xor(mx, 32));
;     const float mnew = fmaxf(mrun, mx);
;     f32x4 ps4 = {0.f, 0.f, 0.f, 0.f};
;     const float foff = fc - mnew;
; #pragma unroll
;     for (int kt = 0; kt < 4; ++kt) {
;         s[kt] = s[kt] * fsc + foff;
; #pragma unroll
;         for (int j = 0; j < 4; ++j) s[kt][j] = __builtin_amdgcn_exp2f(s[kt][j]);
;         ps4 += s[kt];
;     }
;     const float ps = (ps4.x + ps4.y) + (ps4.z + ps4.w);
;     if (__ballot(mnew != mrun) != 0ull) {
;         const float alpha = __builtin_amdgcn_exp2f(mrun - mnew);
;         lrun *= alpha;
; #pragma unroll
;         for (int dt = 0; dt < 4; ++dt) o[dt] *= alpha;
;     }
.LBB0_614:
	v_max3_f32 v118, v102, v103, v104
	v_max3_f32 v121, v105, v98, v99
	v_max3_f32 v125, v100, v101, v94
	v_max3_f32 v127, v95, v96, v97
	v_max3_f32 v118, v118, v121, v125
	v_max3_f32 v131, v90, v91, v92
	v_max3_f32 v127, v127, v131, v93
	v_max_f32_e32 v118, v118, v127
	v_fma_f32 v118, v114, v118, v120
	v_mov_b32_e32 v121, v118
	s_nop 1
	v_permlane16_swap_b32_e32 v121, v118
	v_max_f32_e32 v118, v118, v121
	v_mov_b32_e32 v121, v118
	s_nop 1
	v_permlane32_swap_b32_e32 v121, v118
	v_max3_f32 v118, v119, v118, v121
	v_cmp_neq_f32_e32 vcc, v118, v119
	s_cbranch_vccz .LBB0_616
	v_sub_f32_e32 v119, v119, v118
	v_exp_f32_e32 v132, v119
	s_nop 0
	v_mul_f32_e32 v117, v117, v132
	v_pk_mul_f32 v[56:57], v[56:57], v[132:133] op_sel_hi:[1,0]
	v_pk_mul_f32 v[54:55], v[54:55], v[132:133] op_sel_hi:[1,0]
	v_pk_mul_f32 v[52:53], v[52:53], v[132:133] op_sel_hi:[1,0]
	v_pk_mul_f32 v[50:51], v[50:51], v[132:133] op_sel_hi:[1,0]
	v_pk_mul_f32 v[44:45], v[44:45], v[132:133] op_sel_hi:[1,0]
	v_pk_mul_f32 v[42:43], v[42:43], v[132:133] op_sel_hi:[1,0]
	v_pk_mul_f32 v[48:49], v[48:49], v[132:133] op_sel_hi:[1,0]
	v_pk_mul_f32 v[46:47], v[46:47], v[132:133] op_sel_hi:[1,0]

; template <int MODE>
; __device__ __forceinline__ void attn_step(const unsigned char* sb, int st, const bf16x8 qf0, const bf16x8 qf1, int t, int p0, bool sel, const float* bias, float cfar, f32x4 (&o)[4], float& mrun, float& lrun,
;                                           int koff, int voff, int q4) {
;     ...
;     float mx = fmaxf(fmaxf(fmaxf(s[0][0], s[0][1]), fmaxf(s[0][2], s[0][3])), fmaxf(fmaxf(s[1][0], s[1][1]), fmaxf(s[1][2], s[1][3])));
;     mx = fmaxf(mx, fmaxf(fmaxf(fmaxf(s[2][0], s[2][1]), fmaxf(s[2][2], s[2][3])), fmaxf(fmaxf(s[3][0], s[3][1]), fmaxf(s[3][2], s[3][3]))));
;     mx = mx * fsc + fc;
;     mx = fmaxf(mx, __shfl_xor(mx, 16)); mx = fmaxf(mx, __shfl_xor(mx, 32));
;     const float mnew = fmaxf(mrun, mx);
;     f32x4 ps4 = {0.f, 0.f, 0.f, 0.f};
;     const float foff = fc - mnew;
; #pragma unroll
;     for (int kt = 0; kt < 4; ++kt) {
;         s[kt] = s[kt] * fsc + foff;
; #pragma unroll
;         for (int j = 0; j < 4; ++j) s[kt][j] = __builtin_amdgcn_exp2f(s[kt][j]);
;         ps4 += s[kt];
;     }
;     const float ps = (ps4.x + ps4.y) + (ps4.z + ps4.w);
;     if (__ballot(mnew != mrun) != 0ull) {
;         const float alpha = __builtin_amdgcn_exp2f(mrun - mnew);
;         lrun *= alpha;
; #pragma unroll
;         for (int dt = 0; dt < 4; ++dt) o[dt] *= alpha;
;     }
.LBB0_631:
	v_max3_f32 v0, v106, v107, v108
	v_max3_f32 v149, v109, v110, v111
	v_max3_f32 v150, v112, v113, v114
	v_max3_f32 v151, v115, v116, v117
	v_max3_f32 v0, v0, v149, v150
	v_max3_f32 v152, v118, v119, v120
	v_max3_f32 v151, v151, v152, v121
	v_max_f32_e32 v0, v0, v151
	v_fma_f32 v0, s10, v0, v148
	v_mov_b32_e32 v149, v0
	s_nop 1
	v_permlane16_swap_b32_e32 v149, v0
	v_max_f32_e32 v0, v0, v149
	v_mov_b32_e32 v149, v0
	s_nop 1
	v_permlane32_swap_b32_e32 v149, v0
	v_max3_f32 v0, v147, v0, v149
	v_cmp_neq_f32_e32 vcc, v0, v147
	s_cbranch_vccz .LBB0_633
	v_sub_f32_e32 v147, v147, v0
	v_exp_f32_e32 v150, v147
	s_nop 0
	v_mul_f32_e32 v146, v146, v150
	v_pk_mul_f32 v[16:17], v[16:17], v[150:151] op_sel_hi:[1,0]
	v_pk_mul_f32 v[14:15], v[14:15], v[150:151] op_sel_hi:[1,0]
	v_pk_mul_f32 v[12:13], v[12:13], v[150:151] op_sel_hi:[1,0]
	v_pk_mul_f32 v[10:11], v[10:11], v[150:151] op_sel_hi:[1,0]
	v_pk_mul_f32 v[8:9], v[8:9], v[150:151] op_sel_hi:[1,0]
	v_pk_mul_f32 v[6:7], v[6:7], v[150:151] op_sel_hi:[1,0]
	v_pk_mul_f32 v[4:5], v[4:5], v[150:151] op_sel_hi:[1,0]
	v_pk_mul_f32 v[2:3], v[2:3], v[150:151] op_sel_hi:[1,0]

; template <int MODE>
; __device__ __forceinline__ void attn_step(const unsigned char* sb, int st, const bf16x8 qf0, const bf16x8 qf1, int t, int p0, bool sel, const float* bias, float cfar, f32x4 (&o)[4], float& mrun, float& lrun,
;                                           int koff, int voff, int q4) {
;     ...
;     float mx = fmaxf(fmaxf(fmaxf(s[0][0], s[0][1]), fmaxf(s[0][2], s[0][3])), fmaxf(fmaxf(s[1][0], s[1][1]), fmaxf(s[1][2], s[1][3])));
;     mx = fmaxf(mx, fmaxf(fmaxf(fmaxf(s[2][0], s[2][1]), fmaxf(s[2][2], s[2][3])), fmaxf(fmaxf(s[3][0], s[3][1]), fmaxf(s[3][2], s[3][3]))));
;     mx = mx * fsc + fc;
;     mx = fmaxf(mx, __shfl_xor(mx, 16)); mx = fmaxf(mx, __shfl_xor(mx, 32));
;     const float mnew = fmaxf(mrun, mx);
;     f32x4 ps4 = {0.f, 0.f, 0.f, 0.f};
;     const float foff = fc - mnew;
; #pragma unroll
;     for (int kt = 0; kt < 4; ++kt) {
;         s[kt] = s[kt] * fsc + foff;
; #pragma unroll
;         for (int j = 0; j < 4; ++j) s[kt][j] = __builtin_amdgcn_exp2f(s[kt][j]);
;         ps4 += s[kt];
;     }
;     const float ps = (ps4.x + ps4.y) + (ps4.z + ps4.w);
;     if (__ballot(mnew != mrun) != 0ull) {
;         const float alpha = __builtin_amdgcn_exp2f(mrun - mnew);
;         lrun *= alpha;
; #pragma unroll
;         for (int dt = 0; dt < 4; ++dt) o[dt] *= alpha;
;     }
.LBB0_644:
	v_max3_f32 v147, v106, v107, v108
	v_max3_f32 v149, v109, v110, v111
	v_max3_f32 v150, v112, v113, v114
	v_max3_f32 v151, v115, v116, v117
	v_max3_f32 v147, v147, v149, v150
	v_max3_f32 v152, v118, v119, v120
	v_max3_f32 v151, v151, v152, v121
	v_max_f32_e32 v147, v147, v151
	v_fma_f32 v147, s10, v147, v148
	v_mov_b32_e32 v149, v147
	s_nop 1
	v_permlane16_swap_b32_e32 v149, v147
	v_max_f32_e32 v147, v147, v149
	v_mov_b32_e32 v149, v147
	s_nop 1
	v_permlane32_swap_b32_e32 v149, v147
	v_max3_f32 v147, v0, v147, v149
	v_cmp_neq_f32_e32 vcc, v147, v0
	s_cbranch_vccz .LBB0_646
	v_sub_f32_e32 v0, v0, v147
	v_exp_f32_e32 v0, v0
	s_nop 0
	v_mul_f32_e32 v146, v146, v0
	v_pk_mul_f32 v[16:17], v[16:17], v[0:1] op_sel_hi:[1,0]
	v_pk_mul_f32 v[14:15], v[14:15], v[0:1] op_sel_hi:[1,0]
	v_pk_mul_f32 v[12:13], v[12:13], v[0:1] op_sel_hi:[1,0]
	v_pk_mul_f32 v[10:11], v[10:11], v[0:1] op_sel_hi:[1,0]
	v_pk_mul_f32 v[8:9], v[8:9], v[0:1] op_sel_hi:[1,0]
	v_pk_mul_f32 v[6:7], v[6:7], v[0:1] op_sel_hi:[1,0]
	v_pk_mul_f32 v[4:5], v[4:5], v[0:1] op_sel_hi:[1,0]
	v_pk_mul_f32 v[2:3], v[2:3], v[0:1] op_sel_hi:[1,0]

; __device__ __forceinline__ void cs_pair(int cu, int su0, int su1, const bf16* KVB, const bf16* w1k, const bf16* w1v, const bf16* w2k, const bf16* w2v, const float* bias1, const float* kn0, bf16* KCN, bf16* VCT, ...
;     ...
;         for (int uu = 0; uu < 2; ++uu) {
;             const int su = uu ? su1 : su0, cc = su >> 3, g = su & 7, r0 = cc * 128;
;             u32x4 vraw[8];
; #pragma unroll
;             for (int i = 0; i < 8; ++i) { const int id = t4 + 256 * i, s = id >> 4, dc = id & 15; vraw[i] = *(const u32x4*)(V + (size_t)(r0 + s) * 1024 + g * 128 + dc * 8); }
;             if (t4 < 128) {
;                 const float* sp = VSTAT + (size_t)(r0 + t4) * 32; float s1 = 0.f, s2 = 0.f;
; #pragma unroll
;                 for (int i = 0; i < 8; ++i) { const f32x4 q = *(const f32x4*)(sp + 4 * i); s1 += q.x + q.z; s2 += q.y + q.w; }
;                 const float mean = s1 * (1.f / 1024.f); float var = s2 * (1.f / 1024.f) - mean * mean; var = var > 0.f ? var : 0.f;
;                 mu[t4] = mean; rs[t4] = rsqrtf(var + EPS);
;             }
;             half_bar(ctr2, target);
; #pragma unroll
;             for (int i = 0; i < 8; ++i) {
;                 const int id = t4 + 256 * i, s = id >> 4, dc = id & 15;
;                 const u32x4 raw = vraw[i];
;                 const float m_ = mu[s], r_ = rs[s];
;                 const f32x4 g0 = *(const f32x4*)(lng + g * 128 + dc * 8), g1 = *(const f32x4*)(lng + g * 128 + dc * 8 + 4), b0 = *(const f32x4*)(lnb + g * 128 + dc * 8), b1 = *(const f32x4*)(lnb + g * 128 + dc * 8 + 4);
.LBB0_700:
	s_and_b64 s[10:11], s[6:7], exec
	v_readlane_b32 s10, v253, 11
	s_cselect_b32 s10, s58, s10
	s_lshl_b32 s11, s10, 4
	s_and_b32 s64, s11, 0xffffff80
	s_lshl_b32 s10, s10, 7
	s_and_b32 s65, s10, 0x380
	v_add_u32_e32 v4, s64, v79
	v_add_u32_e32 v6, s64, v115
	s_lshl_b32 s38, s65, 1
	v_ashrrev_i32_e32 v5, 31, v4
	v_ashrrev_i32_e32 v7, 31, v6
	v_lshl_add_u64 v[2:3], v[80:81], 0, s[38:39]
	v_lshlrev_b64 v[4:5], 11, v[4:5]
	v_lshlrev_b64 v[6:7], 11, v[6:7]
	v_lshl_add_u64 v[4:5], v[2:3], 0, v[4:5]
	v_lshl_add_u64 v[6:7], v[2:3], 0, v[6:7]
	global_load_dwordx4 v[46:49], v[4:5], off
	global_load_dwordx4 v[42:45], v[6:7], off
	v_add_u32_e32 v4, s64, v116
	v_add_u32_e32 v6, s64, v117
	v_ashrrev_i32_e32 v5, 31, v4
	v_ashrrev_i32_e32 v7, 31, v6
	v_lshlrev_b64 v[4:5], 11, v[4:5]
	v_lshlrev_b64 v[6:7], 11, v[6:7]
	v_lshl_add_u64 v[4:5], v[2:3], 0, v[4:5]
	v_lshl_add_u64 v[6:7], v[2:3], 0, v[6:7]
	global_load_dwordx4 v[38:41], v[4:5], off
	global_load_dwordx4 v[34:37], v[6:7], off
	v_add_u32_e32 v4, s64, v118
	v_add_u32_e32 v6, s64, v119
	v_ashrrev_i32_e32 v5, 31, v4
	v_ashrrev_i32_e32 v7, 31, v6
	v_lshlrev_b64 v[4:5], 11, v[4:5]
	v_lshlrev_b64 v[6:7], 11, v[6:7]
	v_lshl_add_u64 v[4:5], v[2:3], 0, v[4:5]
	v_lshl_add_u64 v[6:7], v[2:3], 0, v[6:7]
	global_load_dwordx4 v[30:33], v[4:5], off
	global_load_dwordx4 v[10:13], v[6:7], off
	v_add_u32_e32 v4, s64, v120
	v_add_u32_e32 v6, s64, v121
	v_ashrrev_i32_e32 v5, 31, v4
	v_ashrrev_i32_e32 v7, 31, v6
	v_lshlrev_b64 v[4:5], 11, v[4:5]
	v_lshlrev_b64 v[6:7], 11, v[6:7]
	v_lshl_add_u64 v[4:5], v[2:3], 0, v[4:5]
	v_lshl_add_u64 v[2:3], v[2:3], 0, v[6:7]
	global_load_dwordx4 v[6:9], v[4:5], off
	s_nop 0
	global_load_dwordx4 v[2:5], v[2:3], off
	s_and_saveexec_b64 s[10:11], s[0:1]
	s_cbranch_execz .LBB0_702
	v_add_u32_e32 v14, s64, v114
	v_ashrrev_i32_e32 v15, 31, v14
	v_lshlrev_b64 v[14:15], 7, v[14:15]
	v_lshl_add_u64 v[62:63], s[4:5], 0, v[14:15]
	global_load_dwordx4 v[14:17], v[62:63], off
	global_load_dwordx4 v[18:21], v[62:63], off offset:16
	global_load_dwordx4 v[22:25], v[62:63], off offset:32
	global_load_dwordx4 v[26:29], v[62:63], off offset:48
	global_load_dwordx4 v[50:53], v[62:63], off offset:64
	global_load_dwordx4 v[54:57], v[62:63], off offset:80
	global_load_dwordx4 v[58:61], v[62:63], off offset:96
	s_nop 0
	global_load_dwordx4 v[62:65], v[62:63], off offset:112
	s_mov_b32 s12, 0x3a800000
	s_waitcnt vmcnt(7)
	v_pk_add_f32 v[14:15], v[14:15], v[16:17]
	s_waitcnt vmcnt(6)
	v_pk_add_f32 v[16:17], v[18:19], v[20:21]
	v_pk_add_f32 v[14:15], v[14:15], 0 op_sel_hi:[1,0]
	s_waitcnt vmcnt(5)
	v_pk_add_f32 v[18:19], v[22:23], v[24:25]
	v_pk_add_f32 v[14:15], v[14:15], v[16:17]
	s_waitcnt vmcnt(4)
	v_pk_add_f32 v[20:21], v[26:27], v[28:29]
	v_pk_add_f32 v[14:15], v[14:15], v[18:19]
	s_waitcnt vmcnt(3)
	v_pk_add_f32 v[22:23], v[50:51], v[52:53]
	v_pk_add_f32 v[14:15], v[14:15], v[20:21]
	s_waitcnt vmcnt(2)
	v_pk_add_f32 v[24:25], v[54:55], v[56:57]
	v_pk_add_f32 v[14:15], v[14:15], v[22:23]
	s_waitcnt vmcnt(1)
	v_pk_add_f32 v[26:27], v[58:59], v[60:61]
	v_pk_add_f32 v[14:15], v[14:15], v[24:25]
	s_waitcnt vmcnt(0)
	v_pk_add_f32 v[28:29], v[62:63], v[64:65]
	v_pk_add_f32 v[14:15], v[14:15], v[26:27]
	s_nop 0
	v_pk_add_f32 v[14:15], v[14:15], v[28:29]
	s_nop 0
	v_pk_mul_f32 v[14:15], v[14:15], s[12:13] op_sel_hi:[1,0]
	s_nop 0
	v_fma_f32 v0, -v14, v14, v15
	v_max_f32_e32 v0, 0, v0
	v_add_f32_e32 v0, 0x358637bd, v0
	v_mul_f32_e32 v15, 0x4b800000, v0
	v_cmp_gt_f32_e32 vcc, s92, v0
	s_nop 1
	v_cndmask_b32_e32 v0, v0, v15, vcc
	v_rsq_f32_e32 v0, v0
	s_nop 0
	v_mul_f32_e32 v15, 0x45800000, v0
	v_cndmask_b32_e32 v0, v0, v15, vcc
	ds_write2st64_b32 v113, v14, v0 offset0:32 offset1:34
.LBB0_702:
	s_or_b64 exec, exec, s[10:11]
	s_lshl_b32 s12, s65, 2
	s_mov_b32 s13, s39
	v_lshl_add_u64 v[14:15], v[82:83], 0, s[12:13]
	v_lshl_add_u64 v[18:19], v[84:85], 0, s[12:13]
	global_load_dwordx4 v[22:25], v[18:19], off
	global_load_dwordx4 v[26:29], v[14:15], off
	s_nop 0
	global_load_dwordx4 v[14:17], v[14:15], off offset:16
	s_nop 0
	global_load_dwordx4 v[18:21], v[18:19], off offset:16
	s_waitcnt lgkmcnt(0)
	s_mov_b64 s[10:11], exec
	v_readlane_b32 s12, v254, 56
	v_readlane_b32 s13, v254, 57
	s_and_b64 s[12:13], s[10:11], s[12:13]
	s_mov_b64 exec, s[12:13]
	s_cbranch_execz .LBB0_705
	s_mov_b64 s[12:13], exec
	v_mbcnt_lo_u32_b32 v0, s12, 0
	v_mbcnt_hi_u32_b32 v0, s13, v0
	v_cmp_eq_u32_e32 vcc, 0, v0
	s_and_b64 s[36:37], exec, vcc
	s_mov_b64 exec, s[36:37]
	s_cbranch_execz .LBB0_705
	s_bcnt1_i32_b64 s12, s[12:13]
	v_mov_b32_e32 v0, s12
	s_waitcnt vmcnt(0)
	ds_add_u32 v1, v0 offset:8452

; __device__ __forceinline__ bf16 f2bf(float f) { return (bf16)(cvtpk(f, 0.f) & 0xffffu); }
; __device__ __forceinline__ void cs_pair(int cu, int su0, int su1, const bf16* KVB, const bf16* w1k, const bf16* w1v, const bf16* w2k, const bf16* w2v, const float* bias1, const float* kn0, bf16* KCN, bf16* VCT, ...
;     ...
;             half_bar(ctr2, target);
; #pragma unroll
;             for (int i = 0; i < 8; ++i) {
;                 const int id = t4 + 256 * i, s = id >> 4, dc = id & 15;
;                 const u32x4 raw = vraw[i];
;                 const float m_ = mu[s], r_ = rs[s];
;                 const f32x4 g0 = *(const f32x4*)(lng + g * 128 + dc * 8), g1 = *(const f32x4*)(lng + g * 128 + dc * 8 + 4), b0 = *(const f32x4*)(lnb + g * 128 + dc * 8), b1 = *(const f32x4*)(lnb + g * 128 + dc * 8 + 4);
;                 const float gp[8] = {g0.x, g0.y, g0.z, g0.w, g1.x, g1.y, g1.z, g1.w}, bp[8] = {b0.x, b0.y, b0.z, b0.w, b1.x, b1.y, b1.z, b1.w};
;                 float v[8] = {bflo(raw.x), bfhi(raw.x), bflo(raw.y), bfhi(raw.y), bflo(raw.z), bfhi(raw.z), bflo(raw.w), bfhi(raw.w)};
; #pragma unroll
;                 for (int e = 0; e < 8; ++e) vnT[(dc * 8 + e) * 136 + ((((s >> 3) ^ dc) << 3) | (s & 7))] = f2bf((v[e] - m_) * r_ * gp[e] + bp[e]);
;             }
.LBB0_706:
	s_waitcnt vmcnt(0)
	ds_read_b32 v0, v1 offset:8452
	s_waitcnt lgkmcnt(0)
	v_cmp_gt_u32_e32 vcc, s6, v0
	s_cbranch_vccnz .LBB0_706
	s_lshl_b32 s6, s65, 2
	s_mov_b32 s7, s39
	s_waitcnt vmcnt(11)
	v_lshlrev_b32_e32 v0, 16, v46
	v_and_b32_e32 v50, 0xffff0000, v46
	v_lshlrev_b32_e32 v51, 16, v47
	v_and_b32_e32 v52, 0xffff0000, v47
	ds_read2st64_b32 v[46:47], v122 offset0:36 offset1:38
	s_waitcnt vmcnt(10)
	v_lshlrev_b32_e32 v55, 16, v42
	v_and_b32_e32 v56, 0xffff0000, v42
	v_lshlrev_b32_e32 v57, 16, v43
	v_and_b32_e32 v58, 0xffff0000, v43
	ds_read2st64_b32 v[42:43], v123 offset0:36 offset1:38
	v_lshlrev_b32_e32 v53, 16, v48
	v_and_b32_e32 v48, 0xffff0000, v48
	v_lshlrev_b32_e32 v54, 16, v49
	v_and_b32_e32 v49, 0xffff0000, v49
	s_waitcnt lgkmcnt(1)
	v_sub_f32_e32 v0, v0, v46
	v_sub_f32_e32 v50, v50, v46
	v_sub_f32_e32 v51, v51, v46
	v_sub_f32_e32 v52, v52, v46
	v_sub_f32_e32 v53, v53, v46
	v_sub_f32_e32 v48, v48, v46
	v_sub_f32_e32 v54, v54, v46
	v_sub_f32_e32 v46, v49, v46
	s_waitcnt lgkmcnt(0)
	v_sub_f32_e32 v49, v55, v42
	v_sub_f32_e32 v55, v56, v42
	v_sub_f32_e32 v56, v57, v42
	v_sub_f32_e32 v57, v58, v42
	v_mul_f32_e32 v0, v47, v0
	v_mul_f32_e32 v50, v47, v50
	v_mul_f32_e32 v51, v47, v51
	v_mul_f32_e32 v52, v47, v52
	v_mul_f32_e32 v53, v47, v53
	v_mul_f32_e32 v48, v47, v48
	v_mul_f32_e32 v54, v47, v54
	v_mul_f32_e32 v46, v47, v46
	v_mul_f32_e32 v47, v43, v49
	v_mul_f32_e32 v49, v43, v55
	v_mul_f32_e32 v55, v43, v56
	v_mul_f32_e32 v56, v43, v57
	v_lshlrev_b32_e32 v59, 16, v44
	v_and_b32_e32 v44, 0xffff0000, v44
	v_lshlrev_b32_e32 v60, 16, v45
	v_and_b32_e32 v45, 0xffff0000, v45
	s_waitcnt vmcnt(2)
	v_fma_f32 v0, v0, v26, v22
	v_fma_f32 v50, v50, v27, v23
	v_fma_f32 v51, v51, v28, v24
	v_fma_f32 v52, v52, v29, v25
	s_waitcnt vmcnt(0)
	v_fma_f32 v53, v53, v14, v18
	v_fma_f32 v48, v48, v15, v19
	v_fma_f32 v54, v54, v16, v20
	v_fma_f32 v46, v46, v17, v21
	v_fma_f32 v47, v26, v47, v22
	v_fma_f32 v49, v27, v49, v23
	v_fma_f32 v55, v28, v55, v24
	v_fma_f32 v56, v29, v56, v25
	v_cvt_pk_bf16_f32 v0, v0, s0
	v_cvt_pk_bf16_f32 v50, v50, s0
	v_cvt_pk_bf16_f32 v51, v51, s0
	v_cvt_pk_bf16_f32 v52, v52, s0
	v_cvt_pk_bf16_f32 v53, v53, s0
	v_cvt_pk_bf16_f32 v48, v48, s0
	v_cvt_pk_bf16_f32 v54, v54, s0
	v_cvt_pk_bf16_f32 v46, v46, s0
	v_cvt_pk_bf16_f32 v47, v47, s0
	v_cvt_pk_bf16_f32 v49, v49, s0
	v_cvt_pk_bf16_f32 v55, v55, s0
	ds_write_b16 v132, v0 offset:10240
	ds_write_b16 v132, v50 offset:10512
	ds_write_b16 v132, v51 offset:10784
	ds_write_b16 v132, v52 offset:11056
	ds_write_b16 v132, v53 offset:11328
	ds_write_b16 v132, v48 offset:11600
	ds_write_b16 v132, v54 offset:11872
	ds_write_b16 v132, v46 offset:12144
	ds_write_b16 v133, v47 offset:10240
	ds_write_b16 v133, v49 offset:10512
	ds_write_b16 v133, v55 offset:10784
	v_cvt_pk_bf16_f32 v0, v56, s0
	ds_write_b16 v133, v0 offset:11056
	v_sub_f32_e32 v0, v59, v42
	v_mul_f32_e32 v0, v43, v0
	v_fma_f32 v0, v14, v0, v18
	v_cvt_pk_bf16_f32 v0, v0, s0
	ds_write_b16 v133, v0 offset:11328
	v_sub_f32_e32 v0, v44, v42
	v_mul_f32_e32 v0, v43, v0
	v_fma_f32 v0, v15, v0, v19
	v_cvt_pk_bf16_f32 v0, v0, s0
	ds_write_b16 v133, v0 offset:11600
	v_sub_f32_e32 v0, v60, v42
	v_mul_f32_e32 v0, v43, v0
	v_fma_f32 v0, v16, v0, v20
	v_cvt_pk_bf16_f32 v0, v0, s0
	ds_write_b16 v133, v0 offset:11872
	v_sub_f32_e32 v0, v45, v42
	v_mul_f32_e32 v0, v43, v0
	ds_read2st64_b32 v[42:43], v124 offset0:36 offset1:38
	v_fma_f32 v0, v17, v0, v21
	v_cvt_pk_bf16_f32 v0, v0, s0
	ds_write_b16 v133, v0 offset:12144
	v_lshlrev_b32_e32 v0, 16, v38
	s_waitcnt lgkmcnt(1)
	v_sub_f32_e32 v0, v0, v42
	v_mul_f32_e32 v0, v43, v0
	v_fma_f32 v0, v26, v0, v22
	v_and_b32_e32 v38, 0xffff0000, v38
	v_cvt_pk_bf16_f32 v0, v0, s0
	ds_write_b16 v134, v0 offset:10240
	v_sub_f32_e32 v0, v38, v42
	v_mul_f32_e32 v0, v43, v0
	v_fma_f32 v0, v27, v0, v23
	v_lshlrev_b32_e32 v44, 16, v39
	v_cvt_pk_bf16_f32 v0, v0, s0
	ds_write_b16 v134, v0 offset:10512
	v_sub_f32_e32 v0, v44, v42
	v_mul_f32_e32 v0, v43, v0
	v_fma_f32 v0, v28, v0, v24
	v_and_b32_e32 v39, 0xffff0000, v39
	v_cvt_pk_bf16_f32 v0, v0, s0
	ds_write_b16 v134, v0 offset:10784
	v_sub_f32_e32 v0, v39, v42
	v_mul_f32_e32 v0, v43, v0
	v_fma_f32 v0, v29, v0, v25
	v_lshlrev_b32_e32 v45, 16, v40
	v_cvt_pk_bf16_f32 v0, v0, s0
	ds_write_b16 v134, v0 offset:11056
	v_sub_f32_e32 v0, v45, v42
	v_mul_f32_e32 v0, v43, v0
	v_fma_f32 v0, v14, v0, v18
	v_and_b32_e32 v40, 0xffff0000, v40
	v_cvt_pk_bf16_f32 v0, v0, s0
	ds_write_b16 v134, v0 offset:11328
	v_sub_f32_e32 v0, v40, v42
	v_mul_f32_e32 v0, v43, v0
	v_fma_f32 v0, v15, v0, v19
	v_lshlrev_b32_e32 v46, 16, v41
	v_cvt_pk_bf16_f32 v0, v0, s0
	ds_write_b16 v134, v0 offset:11600
	v_sub_f32_e32 v0, v46, v42
	v_mul_f32_e32 v0, v43, v0
	v_fma_f32 v0, v16, v0, v20
	v_and_b32_e32 v41, 0xffff0000, v41
	v_cvt_pk_bf16_f32 v0, v0, s0
	ds_write_b16 v134, v0 offset:11872
	v_sub_f32_e32 v0, v41, v42
	ds_read2st64_b32 v[38:39], v125 offset0:36 offset1:38
	v_mul_f32_e32 v0, v43, v0
	v_fma_f32 v0, v17, v0, v21
	v_cvt_pk_bf16_f32 v0, v0, s0
	ds_write_b16 v134, v0 offset:12144
	v_lshlrev_b32_e32 v0, 16, v34
	s_waitcnt lgkmcnt(1)
; __device__ __forceinline__ bf16 f2bf(float f) { return (bf16)(cvtpk(f, 0.f) & 0xffffu); }
; __device__ __forceinline__ void cs_pair(int cu, int su0, int su1, const bf16* KVB, const bf16* w1k, const bf16* w1v, const bf16* w2k, const bf16* w2v, const float* bias1, const float* kn0, bf16* KCN, bf16* VCT, ...
;     ...
;             for (int i = 0; i < 8; ++i) {
;                 const int id = t4 + 256 * i, s = id >> 4, dc = id & 15;
;                 const u32x4 raw = vraw[i];
;                 const float m_ = mu[s], r_ = rs[s];
;                 const f32x4 g0 = *(const f32x4*)(lng + g * 128 + dc * 8), g1 = *(const f32x4*)(lng + g * 128 + dc * 8 + 4), b0 = *(const f32x4*)(lnb + g * 128 + dc * 8), b1 = *(const f32x4*)(lnb + g * 128 + dc * 8 + 4);
;                 const float gp[8] = {g0.x, g0.y, g0.z, g0.w, g1.x, g1.y, g1.z, g1.w}, bp[8] = {b0.x, b0.y, b0.z, b0.w, b1.x, b1.y, b1.z, b1.w};
;                 float v[8] = {bflo(raw.x), bfhi(raw.x), bflo(raw.y), bfhi(raw.y), bflo(raw.z), bfhi(raw.z), bflo(raw.w), bfhi(raw.w)};
; #pragma unroll
;                 for (int e = 0; e < 8; ++e) vnT[(dc * 8 + e) * 136 + ((((s >> 3) ^ dc) << 3) | (s & 7))] = f2bf((v[e] - m_) * r_ * gp[e] + bp[e]);
;             }
	v_sub_f32_e32 v0, v0, v38
	v_mul_f32_e32 v0, v39, v0
	v_fma_f32 v0, v26, v0, v22
	v_and_b32_e32 v34, 0xffff0000, v34
	v_cvt_pk_bf16_f32 v0, v0, s0
	ds_write_b16 v135, v0 offset:10240
	v_sub_f32_e32 v0, v34, v38
	v_mul_f32_e32 v0, v39, v0
	v_fma_f32 v0, v27, v0, v23
	v_lshlrev_b32_e32 v40, 16, v35
	v_cvt_pk_bf16_f32 v0, v0, s0
	ds_write_b16 v135, v0 offset:10512
	v_sub_f32_e32 v0, v40, v38
	v_mul_f32_e32 v0, v39, v0
	v_fma_f32 v0, v28, v0, v24
	v_and_b32_e32 v35, 0xffff0000, v35
	v_cvt_pk_bf16_f32 v0, v0, s0
	ds_write_b16 v135, v0 offset:10784
	v_sub_f32_e32 v0, v35, v38
	v_mul_f32_e32 v0, v39, v0
	v_fma_f32 v0, v29, v0, v25
	v_lshlrev_b32_e32 v41, 16, v36
	v_cvt_pk_bf16_f32 v0, v0, s0
	ds_write_b16 v135, v0 offset:11056
	v_sub_f32_e32 v0, v41, v38
	v_mul_f32_e32 v0, v39, v0
	v_fma_f32 v0, v14, v0, v18
	v_and_b32_e32 v36, 0xffff0000, v36
	v_cvt_pk_bf16_f32 v0, v0, s0
	ds_write_b16 v135, v0 offset:11328
	v_sub_f32_e32 v0, v36, v38
	v_mul_f32_e32 v0, v39, v0
	v_fma_f32 v0, v15, v0, v19
	v_lshlrev_b32_e32 v42, 16, v37
	v_cvt_pk_bf16_f32 v0, v0, s0
	ds_write_b16 v135, v0 offset:11600
	v_sub_f32_e32 v0, v42, v38
	v_mul_f32_e32 v0, v39, v0
	v_fma_f32 v0, v16, v0, v20
	v_and_b32_e32 v37, 0xffff0000, v37
	v_cvt_pk_bf16_f32 v0, v0, s0
	ds_write_b16 v135, v0 offset:11872
	v_sub_f32_e32 v0, v37, v38
	ds_read2st64_b32 v[34:35], v126 offset0:36 offset1:38
	v_mul_f32_e32 v0, v39, v0
	v_fma_f32 v0, v17, v0, v21
	v_cvt_pk_bf16_f32 v0, v0, s0
	ds_write_b16 v135, v0 offset:12144
	v_lshlrev_b32_e32 v0, 16, v30
	s_waitcnt lgkmcnt(1)
	v_sub_f32_e32 v0, v0, v34
	v_mul_f32_e32 v0, v35, v0
	v_fma_f32 v0, v26, v0, v22
	v_and_b32_e32 v30, 0xffff0000, v30
	v_cvt_pk_bf16_f32 v0, v0, s0
	ds_write_b16 v136, v0 offset:10240
	v_sub_f32_e32 v0, v30, v34
	v_mul_f32_e32 v0, v35, v0
	v_fma_f32 v0, v27, v0, v23
	v_lshlrev_b32_e32 v36, 16, v31
	v_cvt_pk_bf16_f32 v0, v0, s0
	ds_write_b16 v136, v0 offset:10512
	v_sub_f32_e32 v0, v36, v34
	v_mul_f32_e32 v0, v35, v0
	v_fma_f32 v0, v28, v0, v24
	v_and_b32_e32 v31, 0xffff0000, v31
	v_cvt_pk_bf16_f32 v0, v0, s0
	ds_write_b16 v136, v0 offset:10784
	v_sub_f32_e32 v0, v31, v34
	v_mul_f32_e32 v0, v35, v0
	v_fma_f32 v0, v29, v0, v25
	v_lshlrev_b32_e32 v37, 16, v32
	v_cvt_pk_bf16_f32 v0, v0, s0
	ds_write_b16 v136, v0 offset:11056
	v_sub_f32_e32 v0, v37, v34
	v_mul_f32_e32 v0, v35, v0
	v_fma_f32 v0, v14, v0, v18
	v_and_b32_e32 v32, 0xffff0000, v32
	v_cvt_pk_bf16_f32 v0, v0, s0
	ds_write_b16 v136, v0 offset:11328
	v_sub_f32_e32 v0, v32, v34
	v_mul_f32_e32 v0, v35, v0
	v_fma_f32 v0, v15, v0, v19
	v_lshlrev_b32_e32 v38, 16, v33
	v_cvt_pk_bf16_f32 v0, v0, s0
	ds_write_b16 v136, v0 offset:11600
	v_sub_f32_e32 v0, v38, v34
	v_mul_f32_e32 v0, v35, v0
	v_fma_f32 v0, v16, v0, v20
	v_and_b32_e32 v33, 0xffff0000, v33
	v_cvt_pk_bf16_f32 v0, v0, s0
	ds_write_b16 v136, v0 offset:11872
	v_sub_f32_e32 v0, v33, v34
	ds_read2st64_b32 v[30:31], v127 offset0:36 offset1:38
	v_mul_f32_e32 v0, v35, v0
	v_fma_f32 v0, v17, v0, v21
	v_cvt_pk_bf16_f32 v0, v0, s0
	ds_write_b16 v136, v0 offset:12144
	v_lshlrev_b32_e32 v0, 16, v10
	s_waitcnt lgkmcnt(1)
	v_sub_f32_e32 v0, v0, v30
	v_mul_f32_e32 v0, v31, v0
	v_fma_f32 v0, v26, v0, v22
	v_and_b32_e32 v10, 0xffff0000, v10
	v_cvt_pk_bf16_f32 v0, v0, s0
	ds_write_b16 v137, v0 offset:10240
	v_sub_f32_e32 v0, v10, v30
	v_mul_f32_e32 v0, v31, v0
	v_fma_f32 v0, v27, v0, v23
	v_lshlrev_b32_e32 v32, 16, v11
	v_cvt_pk_bf16_f32 v0, v0, s0
	ds_write_b16 v137, v0 offset:10512
	v_sub_f32_e32 v0, v32, v30
	v_mul_f32_e32 v0, v31, v0
	v_fma_f32 v0, v28, v0, v24
	v_and_b32_e32 v11, 0xffff0000, v11
	v_cvt_pk_bf16_f32 v0, v0, s0
	ds_write_b16 v137, v0 offset:10784
	v_sub_f32_e32 v0, v11, v30
	v_mul_f32_e32 v0, v31, v0
	v_fma_f32 v0, v29, v0, v25
	v_lshlrev_b32_e32 v33, 16, v12
	v_cvt_pk_bf16_f32 v0, v0, s0
	ds_write_b16 v137, v0 offset:11056
	v_sub_f32_e32 v0, v33, v30
	v_mul_f32_e32 v0, v31, v0
	v_fma_f32 v0, v14, v0, v18
	v_and_b32_e32 v12, 0xffff0000, v12
	v_cvt_pk_bf16_f32 v0, v0, s0
	ds_write_b16 v137, v0 offset:11328
	v_sub_f32_e32 v0, v12, v30
	v_mul_f32_e32 v0, v31, v0
	v_fma_f32 v0, v15, v0, v19
	v_lshlrev_b32_e32 v34, 16, v13
	v_cvt_pk_bf16_f32 v0, v0, s0
	ds_write_b16 v137, v0 offset:11600
	v_sub_f32_e32 v0, v34, v30
	v_mul_f32_e32 v0, v31, v0
	v_fma_f32 v0, v16, v0, v20
	v_and_b32_e32 v13, 0xffff0000, v13
	v_cvt_pk_bf16_f32 v0, v0, s0
	ds_write_b16 v137, v0 offset:11872
	v_sub_f32_e32 v0, v13, v30
	ds_read2st64_b32 v[10:11], v128 offset0:36 offset1:38
	v_mul_f32_e32 v0, v31, v0
	v_fma_f32 v0, v17, v0, v21
	v_cvt_pk_bf16_f32 v0, v0, s0
	ds_write_b16 v137, v0 offset:12144
	v_lshlrev_b32_e32 v0, 16, v6
	s_waitcnt lgkmcnt(1)
; #define LAS __attribute__((address_space(3)))
; __device__ __forceinline__ bf16 f2bf(float f) { return (bf16)(cvtpk(f, 0.f) & 0xffffu); }
; __device__ __forceinline__ void half_bar(LAS unsigned* ctr, unsigned& target) {
;     target += 4u;
;     asm volatile("s_waitcnt lgkmcnt(0)" ::: "memory");
;     if ((threadIdx.x & 63) == 0) (void)__hip_atomic_fetch_add(ctr, 1u, __ATOMIC_RELAXED, __HIP_MEMORY_SCOPE_WORKGROUP);
;     while (__hip_atomic_load(ctr, __ATOMIC_RELAXED, __HIP_MEMORY_SCOPE_WORKGROUP) < target) { }
; __device__ __forceinline__ void cs_pair(int cu, int su0, int su1, const bf16* KVB, const bf16* w1k, const bf16* w1v, const bf16* w2k, const bf16* w2v, const float* bias1, const float* kn0, bf16* KCN, bf16* VCT, ...
;     ...
;             for (int i = 0; i < 8; ++i) {
;                 const int id = t4 + 256 * i, s = id >> 4, dc = id & 15;
;                 const u32x4 raw = vraw[i];
;                 const float m_ = mu[s], r_ = rs[s];
;                 const f32x4 g0 = *(const f32x4*)(lng + g * 128 + dc * 8), g1 = *(const f32x4*)(lng + g * 128 + dc * 8 + 4), b0 = *(const f32x4*)(lnb + g * 128 + dc * 8), b1 = *(const f32x4*)(lnb + g * 128 + dc * 8 + 4);
;                 const float gp[8] = {g0.x, g0.y, g0.z, g0.w, g1.x, g1.y, g1.z, g1.w}, bp[8] = {b0.x, b0.y, b0.z, b0.w, b1.x, b1.y, b1.z, b1.w};
;                 float v[8] = {bflo(raw.x), bfhi(raw.x), bflo(raw.y), bfhi(raw.y), bflo(raw.z), bfhi(raw.z), bflo(raw.w), bfhi(raw.w)};
; #pragma unroll
;                 for (int e = 0; e < 8; ++e) vnT[(dc * 8 + e) * 136 + ((((s >> 3) ^ dc) << 3) | (s & 7))] = f2bf((v[e] - m_) * r_ * gp[e] + bp[e]);
;             }
;             half_bar(ctr2, target);
	v_sub_f32_e32 v0, v0, v10
	v_mul_f32_e32 v0, v11, v0
	v_fma_f32 v0, v26, v0, v22
	v_and_b32_e32 v6, 0xffff0000, v6
	v_cvt_pk_bf16_f32 v0, v0, s0
	ds_write_b16 v138, v0 offset:10240
	v_sub_f32_e32 v0, v6, v10
	v_mul_f32_e32 v0, v11, v0
	v_fma_f32 v0, v27, v0, v23
	v_lshlrev_b32_e32 v12, 16, v7
	v_cvt_pk_bf16_f32 v0, v0, s0
	ds_write_b16 v138, v0 offset:10512
	v_sub_f32_e32 v0, v12, v10
	v_mul_f32_e32 v0, v11, v0
	v_fma_f32 v0, v28, v0, v24
	v_and_b32_e32 v7, 0xffff0000, v7
	v_cvt_pk_bf16_f32 v0, v0, s0
	ds_write_b16 v138, v0 offset:10784
	v_sub_f32_e32 v0, v7, v10
	v_mul_f32_e32 v0, v11, v0
	v_fma_f32 v0, v29, v0, v25
	v_lshlrev_b32_e32 v13, 16, v8
	v_cvt_pk_bf16_f32 v0, v0, s0
	ds_write_b16 v138, v0 offset:11056
	v_sub_f32_e32 v0, v13, v10
	v_mul_f32_e32 v0, v11, v0
	v_fma_f32 v0, v14, v0, v18
	v_and_b32_e32 v8, 0xffff0000, v8
	v_cvt_pk_bf16_f32 v0, v0, s0
	ds_write_b16 v138, v0 offset:11328
	v_sub_f32_e32 v0, v8, v10
	v_mul_f32_e32 v0, v11, v0
	v_fma_f32 v0, v15, v0, v19
	v_lshlrev_b32_e32 v30, 16, v9
	v_cvt_pk_bf16_f32 v0, v0, s0
	ds_write_b16 v138, v0 offset:11600
	v_sub_f32_e32 v0, v30, v10
	v_mul_f32_e32 v0, v11, v0
	v_fma_f32 v0, v16, v0, v20
	v_and_b32_e32 v9, 0xffff0000, v9
	v_cvt_pk_bf16_f32 v0, v0, s0
	ds_write_b16 v138, v0 offset:11872
	v_sub_f32_e32 v0, v9, v10
	ds_read2st64_b32 v[6:7], v129 offset0:36 offset1:38
	v_mul_f32_e32 v0, v11, v0
	v_fma_f32 v0, v17, v0, v21
	v_cvt_pk_bf16_f32 v0, v0, s0
	ds_write_b16 v138, v0 offset:12144
	v_lshlrev_b32_e32 v0, 16, v2
	s_waitcnt lgkmcnt(1)
	v_sub_f32_e32 v0, v0, v6
	v_mul_f32_e32 v0, v7, v0
	v_fma_f32 v0, v26, v0, v22
	v_and_b32_e32 v2, 0xffff0000, v2
	v_cvt_pk_bf16_f32 v0, v0, s0
	ds_write_b16 v139, v0 offset:10240
	v_sub_f32_e32 v0, v2, v6
	v_mul_f32_e32 v0, v7, v0
	v_fma_f32 v0, v27, v0, v23
	v_lshlrev_b32_e32 v8, 16, v3
	v_cvt_pk_bf16_f32 v0, v0, s0
	ds_write_b16 v139, v0 offset:10512
	v_sub_f32_e32 v0, v8, v6
	v_mul_f32_e32 v0, v7, v0
	v_fma_f32 v0, v28, v0, v24
	v_and_b32_e32 v3, 0xffff0000, v3
	v_cvt_pk_bf16_f32 v0, v0, s0
	ds_write_b16 v139, v0 offset:10784
	v_sub_f32_e32 v0, v3, v6
	v_mul_f32_e32 v0, v7, v0
	v_fmac_f32_e32 v25, v29, v0
	v_lshlrev_b32_e32 v9, 16, v4
	v_cvt_pk_bf16_f32 v0, v25, s0
	ds_write_b16 v139, v0 offset:11056
	v_sub_f32_e32 v0, v9, v6
	v_mul_f32_e32 v0, v7, v0
	v_fma_f32 v0, v14, v0, v18
	v_and_b32_e32 v4, 0xffff0000, v4
	v_cvt_pk_bf16_f32 v0, v0, s0
	ds_write_b16 v139, v0 offset:11328
	v_sub_f32_e32 v0, v4, v6
	v_mul_f32_e32 v0, v7, v0
	v_fma_f32 v0, v15, v0, v19
	v_lshlrev_b32_e32 v10, 16, v5
	v_cvt_pk_bf16_f32 v0, v0, s0
	ds_write_b16 v139, v0 offset:11600
	v_sub_f32_e32 v0, v10, v6
	v_mul_f32_e32 v0, v7, v0
	v_fma_f32 v0, v16, v0, v20
	v_and_b32_e32 v5, 0xffff0000, v5
	v_cvt_pk_bf16_f32 v0, v0, s0
	ds_write_b16 v139, v0 offset:11872
	v_sub_f32_e32 v0, v5, v6
	v_mul_f32_e32 v0, v7, v0
	v_fmac_f32_e32 v21, v17, v0
	v_cvt_pk_bf16_f32 v0, v21, s0
	ds_write_b16 v139, v0 offset:12144
	s_waitcnt lgkmcnt(0)
	s_mov_b64 s[6:7], exec
	v_readlane_b32 s10, v254, 56
	v_readlane_b32 s11, v254, 57
	s_and_b64 s[10:11], s[6:7], s[10:11]
	s_mov_b64 exec, s[10:11]
	s_cbranch_execz .LBB0_710
	s_mov_b64 s[10:11], exec
	v_mbcnt_lo_u32_b32 v0, s10, 0
	v_mbcnt_hi_u32_b32 v0, s11, v0
	v_cmp_eq_u32_e32 vcc, 0, v0
	s_and_b64 s[12:13], exec, vcc
	s_mov_b64 exec, s[12:13]
	s_bcnt1_i32_b64 s10, s[10:11]
	v_mov_b32_e32 v0, s10
	ds_add_u32 v1, v0 offset:8452
